# MLA (tiles by global_load_lds): 4-slot ring, tiles requested three ahead (two in flight, counted vmcnt)
# speedup vs baseline: 1.0111x; 1.0005x over previous
; __device__ __forceinline__ void finishSM9(f32x16& p0, f32x16& p1, float alpha, float& l_reg, v8i32& p8) {
; #pragma unroll
;   for (int r = 0; r < 16; ++r) { p0[r] = __builtin_amdgcn_exp2f(p0[r]); p1[r] = __builtin_amdgcn_exp2f(p1[r]); }
;   float ps = 0;
; #pragma unroll
;   for (int r = 0; r < 16; ++r) ps += p0[r];
; #pragma unroll
;   for (int r = 0; r < 16; ++r) ps += p1[r];
;   { auto rr = __builtin_amdgcn_permlane32_swap(__float_as_uint(ps), __float_as_uint(ps), false, false);
;     ps = __uint_as_float(rr[0]) + __uint_as_float(rr[1]); }
;   l_reg = l_reg * alpha + ps;
; #pragma unroll
;   for (int g = 0; g < 4; ++g) {
;     int w = __builtin_amdgcn_cvt_pk_fp8_f32(p0[4 * g], p0[4 * g + 1], 0, false); p8[g] = __builtin_amdgcn_cvt_pk_fp8_f32(p0[4 * g + 2], p0[4 * g + 3], w, true);
;     int u = __builtin_amdgcn_cvt_pk_fp8_f32(p1[4 * g], p1[4 * g + 1], 0, false); p8[4 + g] = __builtin_amdgcn_cvt_pk_fp8_f32(p1[4 * g + 2], p1[4 * g + 3], u, true); }
; }
; __device__ __forceinline__ void pv8(f32x16* o, const char* Vt, const v8i32 p8, int r32, int hi) {
; __device__ __forceinline__ void attn_unit7(const unsigned char* __restrict__ Q8, int ldq, const unsigned char* __restrict__ Kn8, int ldk, const unsigned char* __restrict__ Kr8, ...
;     ...
;   float m_reg = 0.f, l_reg = 0; f32x16 o[4] = {}; v8i32 qf[3];
;   { const unsigned char* Qw = Q8 + (unsigned)((wid * 32 + r32) * ldq + hi * 32);
; #pragma unroll
;     for (int s = 0; s < 3; ++s) qf[s] = cat8(*reinterpret_cast<const v4i32*>(Qw + s * 64), *reinterpret_cast<const v4i32*>(Qw + s * 64 + 16)); }
;   const int vtr = tid >> 2, vtc = tid & 3, vtst = vtr * 64 + ((vtc ^ ((vtr >> 2) & 3)) << 4);
;   const int knr = tid >> 3, knc = tid & 7, knst = KN8SW(knr, knc);
;   const int krr = (tid >> 2) & 63, krc = tid & 3, krst = KR8SW(krr, krc);
;   const bool krw = tid < 256;
;   unsigned vtoff = (unsigned)(tid * 16), knoff = (unsigned)(knr * ldk + knc * 16), kroff = (unsigned)(krr * 64 + krc * 16);
;   v4i32 vt, kn, kr;
;     ...
;   f32x16 pA0, pA1, pB0, pB1; float alA, alB; v8i32 p8;
;   SLOAD(); SWRITE(0); __syncthreads();
;   SLOAD();
;   qkt9(pA0, pA1, Kn_lds, Kr_lds, qf, 7.0f - m_reg, r32, hi); partialSM9(pA0, pA1, m_reg, alA, thr_raw);
;   SWRITE(1); __syncthreads();
;   for (int j = 1; j + 1 < NT; j += 2) {
;     SLOAD();
;     qkt9(pB0, pB1, Kn_lds + 8192, Kr_lds + 4096, qf, 7.0f - m_reg, r32, hi);
.LBB0_1320:
	s_or_b64 exec, exec, s[20:21]
	v_and_b32_e32 v0, 0x3fffffc0, v12
	s_mov_b32 s20, 0x60000
	v_lshl_add_u32 v187, v0, 2, 0
	v_add3_u32 v178, v13, v14, s20
	v_add_u32_e32 v0, v15, v16
	v_mov_b32_e32 v14, v1
	v_mov_b32_e32 v15, v1
	v_and_b32_e32 v184, 63, v12
	v_lshl_add_u64 v[180:181], s[12:13], 0, v[0:1]
	v_mov_b32_e32 v0, v1
	v_mov_b32_e32 v2, v1
	v_mov_b32_e32 v3, v1
	v_mov_b32_e32 v4, v1
	v_mov_b32_e32 v5, v1
	v_mov_b32_e32 v6, v1
	v_mov_b32_e32 v7, v1
	v_mov_b32_e32 v8, v1
	v_mov_b32_e32 v9, v1
	v_mov_b32_e32 v10, v1
	v_mov_b32_e32 v11, v1
	v_mov_b32_e32 v12, v1
	v_mov_b32_e32 v13, v1
	v_mov_b64_e32 v[64:65], v[14:15]
	v_mov_b64_e32 v[48:49], v[14:15]
	v_mov_b64_e32 v[32:33], v[14:15]
	v_mov_b64_e32 v[62:63], v[12:13]
	v_mov_b64_e32 v[60:61], v[10:11]
	v_mov_b64_e32 v[58:59], v[8:9]
	v_mov_b64_e32 v[56:57], v[6:7]
	v_mov_b64_e32 v[54:55], v[4:5]
	v_mov_b64_e32 v[52:53], v[2:3]
	v_mov_b64_e32 v[50:51], v[0:1]
	v_mov_b64_e32 v[46:47], v[12:13]
	v_mov_b64_e32 v[44:45], v[10:11]
	v_mov_b64_e32 v[42:43], v[8:9]
	v_mov_b64_e32 v[40:41], v[6:7]
	v_mov_b64_e32 v[38:39], v[4:5]
	v_mov_b64_e32 v[36:37], v[2:3]
	v_mov_b64_e32 v[34:35], v[0:1]
	v_mov_b64_e32 v[30:31], v[12:13]
	v_mov_b64_e32 v[28:29], v[10:11]
	v_mov_b64_e32 v[26:27], v[8:9]
	v_mov_b64_e32 v[24:25], v[6:7]
	v_mov_b64_e32 v[22:23], v[4:5]
	v_mov_b64_e32 v[20:21], v[2:3]
	v_mov_b64_e32 v[18:19], v[0:1]
	v_mov_b64_e32 v[16:17], v[14:15]
	s_lshl_b32 s29, s29, 8
	v_cmp_gt_u32_e64 s[40:41], 32, v184
	v_lshl_add_u32 v208, v183, 2, v187
	v_lshlrev_b32_e32 v207, 4, v175
	v_add_u32_e32 v176, 0x6000, v174
	v_mov_b32_e32 v209, 0
	s_mov_b32 s30, -1
	v_mov_b64_e32 v[14:15], v[12:13]
	v_mov_b64_e32 v[12:13], v[10:11]
	v_mov_b64_e32 v[10:11], v[8:9]
	v_mov_b64_e32 v[8:9], v[6:7]
	v_mov_b64_e32 v[6:7], v[4:5]
	v_mov_b64_e32 v[4:5], v[2:3]
	v_mov_b64_e32 v[2:3], v[0:1]
	v_add_u32_e32 v176, 0xffffe000, v176
	v_add_u32_e32 v178, 0xfffe0000, v178
	v_sub_f32_e32 v230, 0x40e00000, v217
	v_mov_b32_e32 v231, v230
	v_mov_b32_e32 v232, v230
	v_mov_b32_e32 v233, v230
	v_mov_b32_e32 v234, v230
	v_mov_b32_e32 v235, v230
	v_mov_b32_e32 v236, v230
	v_mov_b32_e32 v237, v230
	v_mov_b32_e32 v238, v230
	v_mov_b32_e32 v239, v230
	v_mov_b32_e32 v240, v230
	v_mov_b32_e32 v241, v230
	v_mov_b32_e32 v242, v230
	v_mov_b32_e32 v243, v230
	v_mov_b32_e32 v244, v230
	v_mov_b32_e32 v245, v230
	s_mov_b32 s30, 0
	v_lshrrev_b32_e32 v222, 4, v189
	v_and_b32_e32 v223, 3, v222
	v_and_b32_e32 v222, 7, v222
	v_lshlrev_b32_e32 v223, 4, v223
	v_lshlrev_b32_e32 v222, 4, v222
	v_xor_b32_e32 v176, v176, v223
	v_xor_b32_e32 v180, v180, v223
	v_xor_b32_e32 v178, v178, v222
	v_lshrrev_b32_e32 v222, 6, v189
	s_nop 0
	v_readfirstlane_b32 s98, v222
	s_nop 3
	s_lshl_b32 s98, s98, 10
	v_add_u32_e32 v170, 0xa800, v185
	v_add_u32_e32 v171, 0xa800, v186
	v_add_u32_e32 v172, 0xa800, v210
	v_add_u32_e32 v173, 0xa800, v211
	v_add_u32_e32 v220, 0xa800, v212
	v_add_u32_e32 v168, 0xa800, v213
	v_add_u32_e32 v169, 0xa800, v214
	v_add_u32_e32 v166, 0xa800, v215
	v_add_u32_e32 v167, 0xa800, v216
	s_waitcnt lgkmcnt(0)
	s_barrier
	s_cmp_eq_u64 s[42:43], 0
	s_cbranch_scc1 .Lmla_stag_entry
	s_add_i32 m0, s98, 0xa800
	s_nop 0
	global_load_lds_dwordx4 v176, s[18:19]
	s_add_i32 m0, s98, 0xe800
	s_nop 0
	global_load_lds_dwordx4 v178, s[16:17]
	s_add_i32 m0, s98, 0x12800
	s_nop 0
	global_load_lds_dwordx4 v[180:181], off
	v_add_u32_e32 v176, 0x2000, v176
	v_add_u32_e32 v178, 0x20000, v178
	s_mov_b64 s[20:21], 0x1000
	v_lshl_add_u64 v[180:181], v[180:181], 0, s[20:21]
.LBB0_1321:
	ds_read_b128 v[114:117], v215 offset:24576
	ds_read_b128 v[118:121], v216 offset:24576
	ds_read_b128 v[222:225], v215 offset:28672
	ds_read_b128 v[226:229], v216 offset:28672
	s_add_i32 m0, s98, 0xc800
	s_nop 0
	global_load_lds_dwordx4 v176, s[18:19]
	s_add_i32 m0, s98, 0x10800
	s_nop 0
	global_load_lds_dwordx4 v178, s[16:17]
	s_add_i32 m0, s98, 0x13800
	s_nop 0
	global_load_lds_dwordx4 v[180:181], off
	v_add_u32_e32 v176, 0x2000, v176
	v_add_u32_e32 v178, 0x20000, v178
	s_mov_b64 s[20:21], 0x1000
	v_lshl_add_u64 v[180:181], v[180:181], 0, s[20:21]
	v_exp_f32_e32 v0, v82
	v_exp_f32_e32 v177, v83
	v_exp_f32_e32 v179, v84
	v_exp_f32_e32 v254, v85
	v_add_f32_e32 v219, v0, v177
	v_cvt_pk_fp8_f32 v246, v0, v177
	v_add_f32_e32 v219, v179, v219
	v_add_f32_e32 v219, v254, v219
	v_cvt_pk_fp8_f32 v246, v179, v254 op_sel:[0,0,1]
	s_waitcnt lgkmcnt(2)
	v_mfma_scale_f32_32x32x64_f8f6f4 v[114:129], v[114:121], v[146:153], v[230:245], v194, v193 op_sel_hi:[0,0,0]
	v_exp_f32_e32 v0, v86
	v_exp_f32_e32 v177, v87
	v_exp_f32_e32 v179, v88
	v_exp_f32_e32 v254, v89
	v_add_f32_e32 v219, v0, v219
	v_add_f32_e32 v219, v177, v219
	v_cvt_pk_fp8_f32 v247, v0, v177
	v_add_f32_e32 v219, v179, v219
	v_add_f32_e32 v219, v254, v219
	v_cvt_pk_fp8_f32 v247, v179, v254 op_sel:[0,0,1]
	ds_read_b128 v[82:85], v213 offset:24576
	ds_read_b128 v[86:89], v214 offset:24576
	s_waitcnt lgkmcnt(2)
	v_mfma_scale_f32_32x32x64_f8f6f4 v[98:113], v[222:229], v[146:153], v[230:245], v194, v193 op_sel_hi:[0,0,0]
	ds_read_b128 v[222:225], v213 offset:28672
	ds_read_b128 v[226:229], v214 offset:28672
	v_exp_f32_e32 v0, v90
	v_exp_f32_e32 v177, v91
	v_exp_f32_e32 v179, v92
	v_exp_f32_e32 v254, v93
	v_add_f32_e32 v219, v0, v219
	v_add_f32_e32 v219, v177, v219
	v_cvt_pk_fp8_f32 v248, v0, v177
	v_add_f32_e32 v219, v179, v219
	v_add_f32_e32 v219, v254, v219
	v_cvt_pk_fp8_f32 v248, v179, v254 op_sel:[0,0,1]
	v_exp_f32_e32 v0, v94
	v_exp_f32_e32 v177, v95
	v_exp_f32_e32 v179, v96
	v_exp_f32_e32 v254, v97
	v_add_f32_e32 v219, v0, v219
	v_add_f32_e32 v219, v177, v219
	v_cvt_pk_fp8_f32 v249, v0, v177
	v_add_f32_e32 v219, v179, v219
	v_add_f32_e32 v219, v254, v219
	v_cvt_pk_fp8_f32 v249, v179, v254 op_sel:[0,0,1]
	ds_read_b128 v[90:93], v185 offset:36864
	ds_read_b128 v[94:97], v186 offset:36864
	s_waitcnt lgkmcnt(4)
; __device__ __forceinline__ void finishSM9(f32x16& p0, f32x16& p1, float alpha, float& l_reg, v8i32& p8) {
; #pragma unroll
;   for (int r = 0; r < 16; ++r) { p0[r] = __builtin_amdgcn_exp2f(p0[r]); p1[r] = __builtin_amdgcn_exp2f(p1[r]); }
;   float ps = 0;
; #pragma unroll
;   for (int r = 0; r < 16; ++r) ps += p0[r];
; #pragma unroll
;   for (int r = 0; r < 16; ++r) ps += p1[r];
;   { auto rr = __builtin_amdgcn_permlane32_swap(__float_as_uint(ps), __float_as_uint(ps), false, false);
;     ps = __uint_as_float(rr[0]) + __uint_as_float(rr[1]); }
;   l_reg = l_reg * alpha + ps;
; #pragma unroll
;   for (int g = 0; g < 4; ++g) {
;     int w = __builtin_amdgcn_cvt_pk_fp8_f32(p0[4 * g], p0[4 * g + 1], 0, false); p8[g] = __builtin_amdgcn_cvt_pk_fp8_f32(p0[4 * g + 2], p0[4 * g + 3], w, true);
;     int u = __builtin_amdgcn_cvt_pk_fp8_f32(p1[4 * g], p1[4 * g + 1], 0, false); p8[4 + g] = __builtin_amdgcn_cvt_pk_fp8_f32(p1[4 * g + 2], p1[4 * g + 3], u, true); }
; }
; __device__ __forceinline__ void pv8(f32x16* o, const char* Vt, const v8i32 p8, int r32, int hi) {
;   const int sw = (r32 >> 2) & 3, a0 = r32 * 64 + (((hi * 2) ^ sw) << 4), a1 = r32 * 64 + (((hi * 2 + 1) ^ sw) << 4);
; #pragma unroll
;   for (int d0 = 0; d0 < 4; ++d0) {
;     const v8i32 vf = cat8(*reinterpret_cast<const v4i32*>(Vt + d0 * 2048 + a0), *reinterpret_cast<const v4i32*>(Vt + d0 * 2048 + a1));
;     o[d0] = __builtin_amdgcn_mfma_scale_f32_32x32x64_f8f6f4(p8, vf, o[d0], 0, 0, 0, 127, 0, 127); }
; }
; __device__ __forceinline__ void qkt9(f32x16& p0, f32x16& p1, const char* Kn, const char* Kr, const v8i32* qf, const float init, int r32, int hi) {
; #pragma unroll
;   for (int r = 0; r < 16; ++r) { p0[r] = init; p1[r] = init; }
; #pragma unroll
;   for (int s = 0; s < 2; ++s) { const int c0 = s * 4 + hi * 2;
;     const v8i32 a0 = cat8(*reinterpret_cast<const v4i32*>(Kn + KN8SW(r32, c0)), *reinterpret_cast<const v4i32*>(Kn + KN8SW(r32, c0 + 1)));
;     const v8i32 a1 = cat8(*reinterpret_cast<const v4i32*>(Kn + 4096 + KN8SW(r32, c0)), *reinterpret_cast<const v4i32*>(Kn + 4096 + KN8SW(r32, c0 + 1)));
;     p0 = __builtin_amdgcn_mfma_scale_f32_32x32x64_f8f6f4(a0, qf[s], p0, 0, 0, 0, 127, 0, 124);
;     p1 = __builtin_amdgcn_mfma_scale_f32_32x32x64_f8f6f4(a1, qf[s], p1, 0, 0, 0, 127, 0, 124); }
;   { const int c0 = hi * 2;
	v_mfma_scale_f32_32x32x64_f8f6f4 v[114:129], v[82:89], v[138:145], v[114:129], v194, v193 op_sel_hi:[0,0,0]
	v_exp_f32_e32 v0, v66
	v_exp_f32_e32 v177, v67
	v_exp_f32_e32 v179, v68
	v_exp_f32_e32 v254, v69
	v_add_f32_e32 v219, v0, v219
	v_add_f32_e32 v219, v177, v219
	v_cvt_pk_fp8_f32 v250, v0, v177
	v_add_f32_e32 v219, v179, v219
	v_add_f32_e32 v219, v254, v219
	v_cvt_pk_fp8_f32 v250, v179, v254 op_sel:[0,0,1]
	s_waitcnt lgkmcnt(2)
	v_mfma_scale_f32_32x32x64_f8f6f4 v[98:113], v[222:229], v[138:145], v[98:113], v194, v193 op_sel_hi:[0,0,0]
	ds_read_b128 v[222:225], v185 offset:38912
	ds_read_b128 v[226:229], v186 offset:38912
	v_exp_f32_e32 v0, v70
	v_exp_f32_e32 v177, v71
	v_exp_f32_e32 v179, v72
	v_exp_f32_e32 v254, v73
	v_add_f32_e32 v219, v0, v219
	v_add_f32_e32 v219, v177, v219
	v_cvt_pk_fp8_f32 v251, v0, v177
	v_add_f32_e32 v219, v179, v219
	v_add_f32_e32 v219, v254, v219
	v_cvt_pk_fp8_f32 v251, v179, v254 op_sel:[0,0,1]
	v_exp_f32_e32 v0, v74
	v_exp_f32_e32 v177, v75
	v_exp_f32_e32 v179, v76
	v_exp_f32_e32 v254, v77
	v_add_f32_e32 v219, v0, v219
	v_add_f32_e32 v219, v177, v219
	v_cvt_pk_fp8_f32 v252, v0, v177
	v_add_f32_e32 v219, v179, v219
	v_add_f32_e32 v219, v254, v219
	v_cvt_pk_fp8_f32 v252, v179, v254 op_sel:[0,0,1]
	s_waitcnt lgkmcnt(2)
	v_mfma_scale_f32_32x32x64_f8f6f4 v[114:129], v[90:97], v[130:137], v[114:129], v194, v193 op_sel_hi:[0,0,0]
	v_exp_f32_e32 v0, v78
	v_exp_f32_e32 v177, v79
	v_exp_f32_e32 v179, v80
	v_exp_f32_e32 v254, v81
	v_add_f32_e32 v219, v0, v219
	v_add_f32_e32 v219, v177, v219
	v_cvt_pk_fp8_f32 v253, v0, v177
	v_add_f32_e32 v219, v179, v219
	v_add_f32_e32 v219, v254, v219
	v_cvt_pk_fp8_f32 v253, v179, v254 op_sel:[0,0,1]
	ds_read_b128 v[90:93], v185 offset:0
	ds_read_b128 v[94:97], v186 offset:0
	ds_read_b128 v[82:85], v185 offset:2048
	ds_read_b128 v[86:89], v186 offset:2048
	ds_read_b128 v[74:77], v185 offset:4096
	ds_read_b128 v[78:81], v186 offset:4096
	ds_read_b128 v[66:69], v185 offset:6144
	ds_read_b128 v[70:73], v186 offset:6144
	s_waitcnt lgkmcnt(8)
	v_mfma_scale_f32_32x32x64_f8f6f4 v[98:113], v[222:229], v[130:137], v[98:113], v194, v193 op_sel_hi:[0,0,0]
	v_mov_b32_e32 v0, v219
	s_nop 1
	v_permlane32_swap_b32_e32 v219, v0
	v_add_f32_e32 v219, v219, v0
	v_fma_f32 v209, v209, v218, v219
	v_max_f32_e32 v177, v114, v115
	v_max3_f32 v177, v177, v116, v117
	v_max3_f32 v177, v177, v118, v119
	v_max3_f32 v177, v177, v120, v121
	v_max3_f32 v177, v177, v122, v123
	v_max3_f32 v177, v177, v124, v125
	v_max3_f32 v177, v177, v126, v127
	v_max3_f32 v177, v177, v128, v129
	s_waitcnt lgkmcnt(6)
	v_mfma_scale_f32_32x32x64_f8f6f4 v[50:65], v[246:253], v[90:97], v[50:65], v194, v194 op_sel_hi:[0,0,0]
	s_waitcnt lgkmcnt(4)
	v_mfma_scale_f32_32x32x64_f8f6f4 v[34:49], v[246:253], v[82:89], v[34:49], v194, v194 op_sel_hi:[0,0,0]
	s_waitcnt lgkmcnt(2)
	v_mfma_scale_f32_32x32x64_f8f6f4 v[18:33], v[246:253], v[74:81], v[18:33], v194, v194 op_sel_hi:[0,0,0]
	s_waitcnt lgkmcnt(0)
	v_mfma_scale_f32_32x32x64_f8f6f4 v[2:17], v[246:253], v[66:73], v[2:17], v194, v194 op_sel_hi:[0,0,0]
	s_waitcnt vmcnt(3)
	s_waitcnt lgkmcnt(0)
	s_barrier
	v_max_f32_e32 v0, v98, v99
	v_max3_f32 v0, v0, v100, v101
	v_max3_f32 v0, v0, v102, v103
	v_max3_f32 v0, v0, v104, v105
	v_max3_f32 v0, v0, v106, v107
	v_max3_f32 v0, v0, v108, v109
	v_max3_f32 v0, v0, v110, v111
	v_max3_f32 v0, v0, v112, v113
	v_max_f32_e32 v177, v177, v0
	v_mov_b32_e32 v0, v177
	v_mov_b32_e32 v221, 1.0
	s_nop 0
	v_permlane32_swap_b32_e32 v177, v0
	v_max_f32_e32 v177, v177, v0
	v_cmp_ge_f32_e32 vcc, s90, v177
	s_cmp_eq_u64 vcc, exec
	s_cbranch_scc0 .Lmla_h0_newmax
.Lmla_h0_cont:
	ds_read_b128 v[82:85], v166 offset:16384
	ds_read_b128 v[86:89], v167 offset:16384
	ds_read_b128 v[222:225], v166 offset:20480
	ds_read_b128 v[226:229], v167 offset:20480
	s_add_i32 m0, s98, 0x0
	s_nop 0
	global_load_lds_dwordx4 v176, s[18:19]
	s_add_i32 m0, s98, 0x4000
	s_nop 0
	global_load_lds_dwordx4 v178, s[16:17]
	s_add_i32 m0, s98, 0x8000
	s_nop 0
	global_load_lds_dwordx4 v[180:181], off
	v_add_u32_e32 v176, 0x2000, v176
	v_add_u32_e32 v178, 0x20000, v178
	s_mov_b64 s[20:21], 0x1000
	v_lshl_add_u64 v[180:181], v[180:181], 0, s[20:21]
	v_exp_f32_e32 v0, v114
	v_exp_f32_e32 v177, v115
	v_exp_f32_e32 v179, v116
	v_exp_f32_e32 v254, v117
	v_add_f32_e32 v219, v0, v177
	v_cvt_pk_fp8_f32 v246, v0, v177
	v_add_f32_e32 v219, v179, v219
	v_add_f32_e32 v219, v254, v219
	v_cvt_pk_fp8_f32 v246, v179, v254 op_sel:[0,0,1]
	s_waitcnt lgkmcnt(2)
	v_mfma_scale_f32_32x32x64_f8f6f4 v[82:97], v[82:89], v[146:153], v[230:245], v194, v193 op_sel_hi:[0,0,0]
	v_exp_f32_e32 v0, v118
	v_exp_f32_e32 v177, v119
	v_exp_f32_e32 v179, v120
	v_exp_f32_e32 v254, v121
	v_add_f32_e32 v219, v0, v219
	v_add_f32_e32 v219, v177, v219
	v_cvt_pk_fp8_f32 v247, v0, v177
	v_add_f32_e32 v219, v179, v219
	v_add_f32_e32 v219, v254, v219
	v_cvt_pk_fp8_f32 v247, v179, v254 op_sel:[0,0,1]
	ds_read_b128 v[114:117], v168 offset:16384
	ds_read_b128 v[118:121], v169 offset:16384
	s_waitcnt lgkmcnt(2)
	v_mfma_scale_f32_32x32x64_f8f6f4 v[66:81], v[222:229], v[146:153], v[230:245], v194, v193 op_sel_hi:[0,0,0]
	ds_read_b128 v[222:225], v168 offset:20480
	ds_read_b128 v[226:229], v169 offset:20480
	v_exp_f32_e32 v0, v122
	v_exp_f32_e32 v177, v123
	v_exp_f32_e32 v179, v124
	v_exp_f32_e32 v254, v125
	v_add_f32_e32 v219, v0, v219
	v_add_f32_e32 v219, v177, v219
	v_cvt_pk_fp8_f32 v248, v0, v177
	v_add_f32_e32 v219, v179, v219
	v_add_f32_e32 v219, v254, v219
	v_cvt_pk_fp8_f32 v248, v179, v254 op_sel:[0,0,1]
	v_exp_f32_e32 v0, v126
	v_exp_f32_e32 v177, v127
	v_exp_f32_e32 v179, v128
	v_exp_f32_e32 v254, v129
	v_add_f32_e32 v219, v0, v219
	v_add_f32_e32 v219, v177, v219
	v_cvt_pk_fp8_f32 v249, v0, v177
	v_add_f32_e32 v219, v179, v219
	v_add_f32_e32 v219, v254, v219
	v_cvt_pk_fp8_f32 v249, v179, v254 op_sel:[0,0,1]
	ds_read_b128 v[122:125], v170 offset:32768
	ds_read_b128 v[126:129], v171 offset:32768
	s_waitcnt lgkmcnt(4)
; __device__ __forceinline__ void finishSM9(f32x16& p0, f32x16& p1, float alpha, float& l_reg, v8i32& p8) {
; #pragma unroll
;   for (int r = 0; r < 16; ++r) { p0[r] = __builtin_amdgcn_exp2f(p0[r]); p1[r] = __builtin_amdgcn_exp2f(p1[r]); }
;   float ps = 0;
; #pragma unroll
;   for (int r = 0; r < 16; ++r) ps += p0[r];
; #pragma unroll
;   for (int r = 0; r < 16; ++r) ps += p1[r];
;   { auto rr = __builtin_amdgcn_permlane32_swap(__float_as_uint(ps), __float_as_uint(ps), false, false);
;     ps = __uint_as_float(rr[0]) + __uint_as_float(rr[1]); }
;   l_reg = l_reg * alpha + ps;
; #pragma unroll
;   for (int g = 0; g < 4; ++g) {
;     int w = __builtin_amdgcn_cvt_pk_fp8_f32(p0[4 * g], p0[4 * g + 1], 0, false); p8[g] = __builtin_amdgcn_cvt_pk_fp8_f32(p0[4 * g + 2], p0[4 * g + 3], w, true);
;     int u = __builtin_amdgcn_cvt_pk_fp8_f32(p1[4 * g], p1[4 * g + 1], 0, false); p8[4 + g] = __builtin_amdgcn_cvt_pk_fp8_f32(p1[4 * g + 2], p1[4 * g + 3], u, true); }
; }
; __device__ __forceinline__ void pv8(f32x16* o, const char* Vt, const v8i32 p8, int r32, int hi) {
;   const int sw = (r32 >> 2) & 3, a0 = r32 * 64 + (((hi * 2) ^ sw) << 4), a1 = r32 * 64 + (((hi * 2 + 1) ^ sw) << 4);
; #pragma unroll
;   for (int d0 = 0; d0 < 4; ++d0) {
;     const v8i32 vf = cat8(*reinterpret_cast<const v4i32*>(Vt + d0 * 2048 + a0), *reinterpret_cast<const v4i32*>(Vt + d0 * 2048 + a1));
;     o[d0] = __builtin_amdgcn_mfma_scale_f32_32x32x64_f8f6f4(p8, vf, o[d0], 0, 0, 0, 127, 0, 127); }
; }
; __device__ __forceinline__ void qkt9(f32x16& p0, f32x16& p1, const char* Kn, const char* Kr, const v8i32* qf, const float init, int r32, int hi) {
; #pragma unroll
;   for (int r = 0; r < 16; ++r) { p0[r] = init; p1[r] = init; }
; #pragma unroll
;   for (int s = 0; s < 2; ++s) { const int c0 = s * 4 + hi * 2;
;     const v8i32 a0 = cat8(*reinterpret_cast<const v4i32*>(Kn + KN8SW(r32, c0)), *reinterpret_cast<const v4i32*>(Kn + KN8SW(r32, c0 + 1)));
;     const v8i32 a1 = cat8(*reinterpret_cast<const v4i32*>(Kn + 4096 + KN8SW(r32, c0)), *reinterpret_cast<const v4i32*>(Kn + 4096 + KN8SW(r32, c0 + 1)));
;     p0 = __builtin_amdgcn_mfma_scale_f32_32x32x64_f8f6f4(a0, qf[s], p0, 0, 0, 0, 127, 0, 124);
;     p1 = __builtin_amdgcn_mfma_scale_f32_32x32x64_f8f6f4(a1, qf[s], p1, 0, 0, 0, 127, 0, 124); }
;   { const int c0 = hi * 2;
	v_mfma_scale_f32_32x32x64_f8f6f4 v[82:97], v[114:121], v[138:145], v[82:97], v194, v193 op_sel_hi:[0,0,0]
	v_exp_f32_e32 v0, v98
	v_exp_f32_e32 v177, v99
	v_exp_f32_e32 v179, v100
	v_exp_f32_e32 v254, v101
	v_add_f32_e32 v219, v0, v219
	v_add_f32_e32 v219, v177, v219
	v_cvt_pk_fp8_f32 v250, v0, v177
	v_add_f32_e32 v219, v179, v219
	v_add_f32_e32 v219, v254, v219
	v_cvt_pk_fp8_f32 v250, v179, v254 op_sel:[0,0,1]
	s_waitcnt lgkmcnt(2)
	v_mfma_scale_f32_32x32x64_f8f6f4 v[66:81], v[222:229], v[138:145], v[66:81], v194, v193 op_sel_hi:[0,0,0]
	ds_read_b128 v[222:225], v170 offset:34816
	ds_read_b128 v[226:229], v171 offset:34816
	v_exp_f32_e32 v0, v102
	v_exp_f32_e32 v177, v103
	v_exp_f32_e32 v179, v104
	v_exp_f32_e32 v254, v105
	v_add_f32_e32 v219, v0, v219
	v_add_f32_e32 v219, v177, v219
	v_cvt_pk_fp8_f32 v251, v0, v177
	v_add_f32_e32 v219, v179, v219
	v_add_f32_e32 v219, v254, v219
	v_cvt_pk_fp8_f32 v251, v179, v254 op_sel:[0,0,1]
	v_exp_f32_e32 v0, v106
	v_exp_f32_e32 v177, v107
	v_exp_f32_e32 v179, v108
	v_exp_f32_e32 v254, v109
	v_add_f32_e32 v219, v0, v219
	v_add_f32_e32 v219, v177, v219
	v_cvt_pk_fp8_f32 v252, v0, v177
	v_add_f32_e32 v219, v179, v219
	v_add_f32_e32 v219, v254, v219
	v_cvt_pk_fp8_f32 v252, v179, v254 op_sel:[0,0,1]
	s_waitcnt lgkmcnt(2)
	v_mfma_scale_f32_32x32x64_f8f6f4 v[82:97], v[122:129], v[130:137], v[82:97], v194, v193 op_sel_hi:[0,0,0]
	v_exp_f32_e32 v0, v110
	v_exp_f32_e32 v177, v111
	v_exp_f32_e32 v179, v112
	v_exp_f32_e32 v254, v113
	v_add_f32_e32 v219, v0, v219
	v_add_f32_e32 v219, v177, v219
	v_cvt_pk_fp8_f32 v253, v0, v177
	v_add_f32_e32 v219, v179, v219
	v_add_f32_e32 v219, v254, v219
	v_cvt_pk_fp8_f32 v253, v179, v254 op_sel:[0,0,1]
	ds_read_b128 v[122:125], v185 offset:8192
	ds_read_b128 v[126:129], v186 offset:8192
	ds_read_b128 v[114:117], v185 offset:10240
	ds_read_b128 v[118:121], v186 offset:10240
	ds_read_b128 v[106:109], v185 offset:12288
	ds_read_b128 v[110:113], v186 offset:12288
	ds_read_b128 v[98:101], v185 offset:14336
	ds_read_b128 v[102:105], v186 offset:14336
	s_waitcnt lgkmcnt(8)
	v_mfma_scale_f32_32x32x64_f8f6f4 v[66:81], v[222:229], v[130:137], v[66:81], v194, v193 op_sel_hi:[0,0,0]
	v_mov_b32_e32 v0, v219
	s_nop 1
	v_permlane32_swap_b32_e32 v219, v0
	v_add_f32_e32 v219, v219, v0
	v_fma_f32 v209, v209, v221, v219
	v_max_f32_e32 v177, v82, v83
	v_max3_f32 v177, v177, v84, v85
	v_max3_f32 v177, v177, v86, v87
	v_max3_f32 v177, v177, v88, v89
	v_max3_f32 v177, v177, v90, v91
	v_max3_f32 v177, v177, v92, v93
	v_max3_f32 v177, v177, v94, v95
	v_max3_f32 v177, v177, v96, v97
	s_waitcnt lgkmcnt(6)
	v_mfma_scale_f32_32x32x64_f8f6f4 v[50:65], v[246:253], v[122:129], v[50:65], v194, v194 op_sel_hi:[0,0,0]
	s_waitcnt lgkmcnt(4)
	v_mfma_scale_f32_32x32x64_f8f6f4 v[34:49], v[246:253], v[114:121], v[34:49], v194, v194 op_sel_hi:[0,0,0]
	s_waitcnt lgkmcnt(2)
	v_mfma_scale_f32_32x32x64_f8f6f4 v[18:33], v[246:253], v[106:113], v[18:33], v194, v194 op_sel_hi:[0,0,0]
	s_waitcnt lgkmcnt(0)
	v_mfma_scale_f32_32x32x64_f8f6f4 v[2:17], v[246:253], v[98:105], v[2:17], v194, v194 op_sel_hi:[0,0,0]
	s_waitcnt vmcnt(3)
	s_waitcnt lgkmcnt(0)
	s_barrier
	v_max_f32_e32 v0, v66, v67
	v_max3_f32 v0, v0, v68, v69
	v_max3_f32 v0, v0, v70, v71
	v_max3_f32 v0, v0, v72, v73
	v_max3_f32 v0, v0, v74, v75
	v_max3_f32 v0, v0, v76, v77
	v_max3_f32 v0, v0, v78, v79
	v_max3_f32 v0, v0, v80, v81
	v_max_f32_e32 v177, v177, v0
	v_mov_b32_e32 v0, v177
	v_mov_b32_e32 v218, 1.0
	s_nop 0
	v_permlane32_swap_b32_e32 v177, v0
	v_max_f32_e32 v177, v177, v0
	v_cmp_ge_f32_e32 vcc, s90, v177
	s_cmp_eq_u64 vcc, exec
	s_cbranch_scc0 .Lmla_h1_newmax
.Lmla_h1_cont:
	ds_read_b128 v[114:117], v166 offset:24576
	ds_read_b128 v[118:121], v167 offset:24576
	ds_read_b128 v[222:225], v166 offset:28672
	ds_read_b128 v[226:229], v167 offset:28672
	s_add_i32 m0, s98, 0x2000
	s_nop 0
	global_load_lds_dwordx4 v176, s[18:19]
	s_add_i32 m0, s98, 0x6000
	s_nop 0
	global_load_lds_dwordx4 v178, s[16:17]
	s_add_i32 m0, s98, 0x9000
	s_nop 0
	global_load_lds_dwordx4 v[180:181], off
	v_add_u32_e32 v176, 0x2000, v176
	v_add_u32_e32 v178, 0x20000, v178
	s_mov_b64 s[20:21], 0x1000
	v_lshl_add_u64 v[180:181], v[180:181], 0, s[20:21]
	v_exp_f32_e32 v0, v82
	v_exp_f32_e32 v177, v83
	v_exp_f32_e32 v179, v84
	v_exp_f32_e32 v254, v85
	v_add_f32_e32 v219, v0, v177
	v_cvt_pk_fp8_f32 v246, v0, v177
	v_add_f32_e32 v219, v179, v219
	v_add_f32_e32 v219, v254, v219
	v_cvt_pk_fp8_f32 v246, v179, v254 op_sel:[0,0,1]
	s_waitcnt lgkmcnt(2)
	v_mfma_scale_f32_32x32x64_f8f6f4 v[114:129], v[114:121], v[146:153], v[230:245], v194, v193 op_sel_hi:[0,0,0]
	v_exp_f32_e32 v0, v86
	v_exp_f32_e32 v177, v87
	v_exp_f32_e32 v179, v88
	v_exp_f32_e32 v254, v89
	v_add_f32_e32 v219, v0, v219
	v_add_f32_e32 v219, v177, v219
	v_cvt_pk_fp8_f32 v247, v0, v177
	v_add_f32_e32 v219, v179, v219
	v_add_f32_e32 v219, v254, v219
	v_cvt_pk_fp8_f32 v247, v179, v254 op_sel:[0,0,1]
	ds_read_b128 v[82:85], v168 offset:24576
	ds_read_b128 v[86:89], v169 offset:24576
	s_waitcnt lgkmcnt(2)
	v_mfma_scale_f32_32x32x64_f8f6f4 v[98:113], v[222:229], v[146:153], v[230:245], v194, v193 op_sel_hi:[0,0,0]
	ds_read_b128 v[222:225], v168 offset:28672
	ds_read_b128 v[226:229], v169 offset:28672
	v_exp_f32_e32 v0, v90
	v_exp_f32_e32 v177, v91
	v_exp_f32_e32 v179, v92
	v_exp_f32_e32 v254, v93
	v_add_f32_e32 v219, v0, v219
	v_add_f32_e32 v219, v177, v219
	v_cvt_pk_fp8_f32 v248, v0, v177
	v_add_f32_e32 v219, v179, v219
	v_add_f32_e32 v219, v254, v219
	v_cvt_pk_fp8_f32 v248, v179, v254 op_sel:[0,0,1]
	v_exp_f32_e32 v0, v94
	v_exp_f32_e32 v177, v95
	v_exp_f32_e32 v179, v96
	v_exp_f32_e32 v254, v97
	v_add_f32_e32 v219, v0, v219
	v_add_f32_e32 v219, v177, v219
	v_cvt_pk_fp8_f32 v249, v0, v177
	v_add_f32_e32 v219, v179, v219
	v_add_f32_e32 v219, v254, v219
	v_cvt_pk_fp8_f32 v249, v179, v254 op_sel:[0,0,1]
	ds_read_b128 v[90:93], v170 offset:36864
	ds_read_b128 v[94:97], v171 offset:36864
	s_waitcnt lgkmcnt(4)
; __device__ __forceinline__ void finishSM9(f32x16& p0, f32x16& p1, float alpha, float& l_reg, v8i32& p8) {
; #pragma unroll
;   for (int r = 0; r < 16; ++r) { p0[r] = __builtin_amdgcn_exp2f(p0[r]); p1[r] = __builtin_amdgcn_exp2f(p1[r]); }
;   float ps = 0;
; #pragma unroll
;   for (int r = 0; r < 16; ++r) ps += p0[r];
; #pragma unroll
;   for (int r = 0; r < 16; ++r) ps += p1[r];
;   { auto rr = __builtin_amdgcn_permlane32_swap(__float_as_uint(ps), __float_as_uint(ps), false, false);
;     ps = __uint_as_float(rr[0]) + __uint_as_float(rr[1]); }
;   l_reg = l_reg * alpha + ps;
; #pragma unroll
;   for (int g = 0; g < 4; ++g) {
;     int w = __builtin_amdgcn_cvt_pk_fp8_f32(p0[4 * g], p0[4 * g + 1], 0, false); p8[g] = __builtin_amdgcn_cvt_pk_fp8_f32(p0[4 * g + 2], p0[4 * g + 3], w, true);
;     int u = __builtin_amdgcn_cvt_pk_fp8_f32(p1[4 * g], p1[4 * g + 1], 0, false); p8[4 + g] = __builtin_amdgcn_cvt_pk_fp8_f32(p1[4 * g + 2], p1[4 * g + 3], u, true); }
; }
; __device__ __forceinline__ void pv8(f32x16* o, const char* Vt, const v8i32 p8, int r32, int hi) {
;   const int sw = (r32 >> 2) & 3, a0 = r32 * 64 + (((hi * 2) ^ sw) << 4), a1 = r32 * 64 + (((hi * 2 + 1) ^ sw) << 4);
; #pragma unroll
;   for (int d0 = 0; d0 < 4; ++d0) {
;     const v8i32 vf = cat8(*reinterpret_cast<const v4i32*>(Vt + d0 * 2048 + a0), *reinterpret_cast<const v4i32*>(Vt + d0 * 2048 + a1));
;     o[d0] = __builtin_amdgcn_mfma_scale_f32_32x32x64_f8f6f4(p8, vf, o[d0], 0, 0, 0, 127, 0, 127); }
; }
; __device__ __forceinline__ void qkt9(f32x16& p0, f32x16& p1, const char* Kn, const char* Kr, const v8i32* qf, const float init, int r32, int hi) {
; #pragma unroll
;   for (int r = 0; r < 16; ++r) { p0[r] = init; p1[r] = init; }
; #pragma unroll
;   for (int s = 0; s < 2; ++s) { const int c0 = s * 4 + hi * 2;
;     const v8i32 a0 = cat8(*reinterpret_cast<const v4i32*>(Kn + KN8SW(r32, c0)), *reinterpret_cast<const v4i32*>(Kn + KN8SW(r32, c0 + 1)));
;     const v8i32 a1 = cat8(*reinterpret_cast<const v4i32*>(Kn + 4096 + KN8SW(r32, c0)), *reinterpret_cast<const v4i32*>(Kn + 4096 + KN8SW(r32, c0 + 1)));
;     p0 = __builtin_amdgcn_mfma_scale_f32_32x32x64_f8f6f4(a0, qf[s], p0, 0, 0, 0, 127, 0, 124);
;     p1 = __builtin_amdgcn_mfma_scale_f32_32x32x64_f8f6f4(a1, qf[s], p1, 0, 0, 0, 127, 0, 124); }
;   { const int c0 = hi * 2;
	v_mfma_scale_f32_32x32x64_f8f6f4 v[114:129], v[82:89], v[138:145], v[114:129], v194, v193 op_sel_hi:[0,0,0]
	v_exp_f32_e32 v0, v66
	v_exp_f32_e32 v177, v67
	v_exp_f32_e32 v179, v68
	v_exp_f32_e32 v254, v69
	v_add_f32_e32 v219, v0, v219
	v_add_f32_e32 v219, v177, v219
	v_cvt_pk_fp8_f32 v250, v0, v177
	v_add_f32_e32 v219, v179, v219
	v_add_f32_e32 v219, v254, v219
	v_cvt_pk_fp8_f32 v250, v179, v254 op_sel:[0,0,1]
	s_waitcnt lgkmcnt(2)
	v_mfma_scale_f32_32x32x64_f8f6f4 v[98:113], v[222:229], v[138:145], v[98:113], v194, v193 op_sel_hi:[0,0,0]
	ds_read_b128 v[222:225], v170 offset:38912
	ds_read_b128 v[226:229], v171 offset:38912
	v_exp_f32_e32 v0, v70
	v_exp_f32_e32 v177, v71
	v_exp_f32_e32 v179, v72
	v_exp_f32_e32 v254, v73
	v_add_f32_e32 v219, v0, v219
	v_add_f32_e32 v219, v177, v219
	v_cvt_pk_fp8_f32 v251, v0, v177
	v_add_f32_e32 v219, v179, v219
	v_add_f32_e32 v219, v254, v219
	v_cvt_pk_fp8_f32 v251, v179, v254 op_sel:[0,0,1]
	v_exp_f32_e32 v0, v74
	v_exp_f32_e32 v177, v75
	v_exp_f32_e32 v179, v76
	v_exp_f32_e32 v254, v77
	v_add_f32_e32 v219, v0, v219
	v_add_f32_e32 v219, v177, v219
	v_cvt_pk_fp8_f32 v252, v0, v177
	v_add_f32_e32 v219, v179, v219
	v_add_f32_e32 v219, v254, v219
	v_cvt_pk_fp8_f32 v252, v179, v254 op_sel:[0,0,1]
	s_waitcnt lgkmcnt(2)
	v_mfma_scale_f32_32x32x64_f8f6f4 v[114:129], v[90:97], v[130:137], v[114:129], v194, v193 op_sel_hi:[0,0,0]
	v_exp_f32_e32 v0, v78
	v_exp_f32_e32 v177, v79
	v_exp_f32_e32 v179, v80
	v_exp_f32_e32 v254, v81
	v_add_f32_e32 v219, v0, v219
	v_add_f32_e32 v219, v177, v219
	v_cvt_pk_fp8_f32 v253, v0, v177
	v_add_f32_e32 v219, v179, v219
	v_add_f32_e32 v219, v254, v219
	v_cvt_pk_fp8_f32 v253, v179, v254 op_sel:[0,0,1]
	ds_read_b128 v[90:93], v170 offset:0
	ds_read_b128 v[94:97], v171 offset:0
	ds_read_b128 v[82:85], v170 offset:2048
	ds_read_b128 v[86:89], v171 offset:2048
	ds_read_b128 v[74:77], v170 offset:4096
	ds_read_b128 v[78:81], v171 offset:4096
	ds_read_b128 v[66:69], v170 offset:6144
	ds_read_b128 v[70:73], v171 offset:6144
	s_waitcnt lgkmcnt(8)
	v_mfma_scale_f32_32x32x64_f8f6f4 v[98:113], v[222:229], v[130:137], v[98:113], v194, v193 op_sel_hi:[0,0,0]
	v_mov_b32_e32 v0, v219
	s_nop 1
	v_permlane32_swap_b32_e32 v219, v0
	v_add_f32_e32 v219, v219, v0
	v_fma_f32 v209, v209, v218, v219
	v_max_f32_e32 v177, v114, v115
	v_max3_f32 v177, v177, v116, v117
	v_max3_f32 v177, v177, v118, v119
	v_max3_f32 v177, v177, v120, v121
	v_max3_f32 v177, v177, v122, v123
	v_max3_f32 v177, v177, v124, v125
	v_max3_f32 v177, v177, v126, v127
	v_max3_f32 v177, v177, v128, v129
	s_waitcnt lgkmcnt(6)
	v_mfma_scale_f32_32x32x64_f8f6f4 v[50:65], v[246:253], v[90:97], v[50:65], v194, v194 op_sel_hi:[0,0,0]
	s_waitcnt lgkmcnt(4)
	v_mfma_scale_f32_32x32x64_f8f6f4 v[34:49], v[246:253], v[82:89], v[34:49], v194, v194 op_sel_hi:[0,0,0]
	s_waitcnt lgkmcnt(2)
	v_mfma_scale_f32_32x32x64_f8f6f4 v[18:33], v[246:253], v[74:81], v[18:33], v194, v194 op_sel_hi:[0,0,0]
	s_waitcnt lgkmcnt(0)
	v_mfma_scale_f32_32x32x64_f8f6f4 v[2:17], v[246:253], v[66:73], v[2:17], v194, v194 op_sel_hi:[0,0,0]
	s_waitcnt vmcnt(3)
	s_waitcnt lgkmcnt(0)
	s_barrier
	v_max_f32_e32 v0, v98, v99
	v_max3_f32 v0, v0, v100, v101
	v_max3_f32 v0, v0, v102, v103
	v_max3_f32 v0, v0, v104, v105
	v_max3_f32 v0, v0, v106, v107
	v_max3_f32 v0, v0, v108, v109
	v_max3_f32 v0, v0, v110, v111
	v_max3_f32 v0, v0, v112, v113
	v_max_f32_e32 v177, v177, v0
	v_mov_b32_e32 v0, v177
	v_mov_b32_e32 v221, 1.0
	s_nop 0
	v_permlane32_swap_b32_e32 v177, v0
	v_max_f32_e32 v177, v177, v0
	v_cmp_ge_f32_e32 vcc, s90, v177
	s_cmp_eq_u64 vcc, exec
	s_cbranch_scc0 .Lmla_h2_newmax
.Lmla_h2_cont:
	ds_read_b128 v[82:85], v215 offset:16384
	ds_read_b128 v[86:89], v216 offset:16384
	ds_read_b128 v[222:225], v215 offset:20480
	ds_read_b128 v[226:229], v216 offset:20480
	s_add_i32 m0, s98, 0xa800
	s_nop 0
	global_load_lds_dwordx4 v176, s[18:19]
	s_add_i32 m0, s98, 0xe800
	s_nop 0
	global_load_lds_dwordx4 v178, s[16:17]
	s_add_i32 m0, s98, 0x12800
	s_nop 0
	global_load_lds_dwordx4 v[180:181], off
	v_add_u32_e32 v176, 0x2000, v176
	v_add_u32_e32 v178, 0x20000, v178
	s_mov_b64 s[20:21], 0x1000
	v_lshl_add_u64 v[180:181], v[180:181], 0, s[20:21]
	v_exp_f32_e32 v0, v114
	v_exp_f32_e32 v177, v115
	v_exp_f32_e32 v179, v116
	v_exp_f32_e32 v254, v117
	v_add_f32_e32 v219, v0, v177
	v_cvt_pk_fp8_f32 v246, v0, v177
	v_add_f32_e32 v219, v179, v219
	v_add_f32_e32 v219, v254, v219
	v_cvt_pk_fp8_f32 v246, v179, v254 op_sel:[0,0,1]
	s_waitcnt lgkmcnt(2)
	v_mfma_scale_f32_32x32x64_f8f6f4 v[82:97], v[82:89], v[146:153], v[230:245], v194, v193 op_sel_hi:[0,0,0]
	v_exp_f32_e32 v0, v118
	v_exp_f32_e32 v177, v119
	v_exp_f32_e32 v179, v120
	v_exp_f32_e32 v254, v121
	v_add_f32_e32 v219, v0, v219
	v_add_f32_e32 v219, v177, v219
	v_cvt_pk_fp8_f32 v247, v0, v177
	v_add_f32_e32 v219, v179, v219
	v_add_f32_e32 v219, v254, v219
	v_cvt_pk_fp8_f32 v247, v179, v254 op_sel:[0,0,1]
	ds_read_b128 v[114:117], v213 offset:16384
	ds_read_b128 v[118:121], v214 offset:16384
	s_waitcnt lgkmcnt(2)
	v_mfma_scale_f32_32x32x64_f8f6f4 v[66:81], v[222:229], v[146:153], v[230:245], v194, v193 op_sel_hi:[0,0,0]
	ds_read_b128 v[222:225], v213 offset:20480
	ds_read_b128 v[226:229], v214 offset:20480
	v_exp_f32_e32 v0, v122
	v_exp_f32_e32 v177, v123
	v_exp_f32_e32 v179, v124
	v_exp_f32_e32 v254, v125
	v_add_f32_e32 v219, v0, v219
	v_add_f32_e32 v219, v177, v219
	v_cvt_pk_fp8_f32 v248, v0, v177
	v_add_f32_e32 v219, v179, v219
	v_add_f32_e32 v219, v254, v219
	v_cvt_pk_fp8_f32 v248, v179, v254 op_sel:[0,0,1]
	v_exp_f32_e32 v0, v126
	v_exp_f32_e32 v177, v127
	v_exp_f32_e32 v179, v128
	v_exp_f32_e32 v254, v129
	v_add_f32_e32 v219, v0, v219
	v_add_f32_e32 v219, v177, v219
	v_cvt_pk_fp8_f32 v249, v0, v177
	v_add_f32_e32 v219, v179, v219
	v_add_f32_e32 v219, v254, v219
	v_cvt_pk_fp8_f32 v249, v179, v254 op_sel:[0,0,1]
	ds_read_b128 v[122:125], v185 offset:32768
	ds_read_b128 v[126:129], v186 offset:32768
	s_waitcnt lgkmcnt(4)
; __device__ __forceinline__ void finishSM9(f32x16& p0, f32x16& p1, float alpha, float& l_reg, v8i32& p8) {
; #pragma unroll
;   for (int r = 0; r < 16; ++r) { p0[r] = __builtin_amdgcn_exp2f(p0[r]); p1[r] = __builtin_amdgcn_exp2f(p1[r]); }
;   float ps = 0;
; #pragma unroll
;   for (int r = 0; r < 16; ++r) ps += p0[r];
; #pragma unroll
;   for (int r = 0; r < 16; ++r) ps += p1[r];
;   { auto rr = __builtin_amdgcn_permlane32_swap(__float_as_uint(ps), __float_as_uint(ps), false, false);
;     ps = __uint_as_float(rr[0]) + __uint_as_float(rr[1]); }
;   l_reg = l_reg * alpha + ps;
; #pragma unroll
;   for (int g = 0; g < 4; ++g) {
;     int w = __builtin_amdgcn_cvt_pk_fp8_f32(p0[4 * g], p0[4 * g + 1], 0, false); p8[g] = __builtin_amdgcn_cvt_pk_fp8_f32(p0[4 * g + 2], p0[4 * g + 3], w, true);
;     int u = __builtin_amdgcn_cvt_pk_fp8_f32(p1[4 * g], p1[4 * g + 1], 0, false); p8[4 + g] = __builtin_amdgcn_cvt_pk_fp8_f32(p1[4 * g + 2], p1[4 * g + 3], u, true); }
; }
; __device__ __forceinline__ void pv8(f32x16* o, const char* Vt, const v8i32 p8, int r32, int hi) {
;   const int sw = (r32 >> 2) & 3, a0 = r32 * 64 + (((hi * 2) ^ sw) << 4), a1 = r32 * 64 + (((hi * 2 + 1) ^ sw) << 4);
; #pragma unroll
;   for (int d0 = 0; d0 < 4; ++d0) {
;     const v8i32 vf = cat8(*reinterpret_cast<const v4i32*>(Vt + d0 * 2048 + a0), *reinterpret_cast<const v4i32*>(Vt + d0 * 2048 + a1));
;     o[d0] = __builtin_amdgcn_mfma_scale_f32_32x32x64_f8f6f4(p8, vf, o[d0], 0, 0, 0, 127, 0, 127); }
; }
; __device__ __forceinline__ void qkt9(f32x16& p0, f32x16& p1, const char* Kn, const char* Kr, const v8i32* qf, const float init, int r32, int hi) {
; #pragma unroll
;   for (int r = 0; r < 16; ++r) { p0[r] = init; p1[r] = init; }
; #pragma unroll
;   for (int s = 0; s < 2; ++s) { const int c0 = s * 4 + hi * 2;
;     const v8i32 a0 = cat8(*reinterpret_cast<const v4i32*>(Kn + KN8SW(r32, c0)), *reinterpret_cast<const v4i32*>(Kn + KN8SW(r32, c0 + 1)));
;     const v8i32 a1 = cat8(*reinterpret_cast<const v4i32*>(Kn + 4096 + KN8SW(r32, c0)), *reinterpret_cast<const v4i32*>(Kn + 4096 + KN8SW(r32, c0 + 1)));
;     p0 = __builtin_amdgcn_mfma_scale_f32_32x32x64_f8f6f4(a0, qf[s], p0, 0, 0, 0, 127, 0, 124);
;     p1 = __builtin_amdgcn_mfma_scale_f32_32x32x64_f8f6f4(a1, qf[s], p1, 0, 0, 0, 127, 0, 124); }
;   { const int c0 = hi * 2;
	v_mfma_scale_f32_32x32x64_f8f6f4 v[82:97], v[114:121], v[138:145], v[82:97], v194, v193 op_sel_hi:[0,0,0]
	v_exp_f32_e32 v0, v98
	v_exp_f32_e32 v177, v99
	v_exp_f32_e32 v179, v100
	v_exp_f32_e32 v254, v101
	v_add_f32_e32 v219, v0, v219
	v_add_f32_e32 v219, v177, v219
	v_cvt_pk_fp8_f32 v250, v0, v177
	v_add_f32_e32 v219, v179, v219
	v_add_f32_e32 v219, v254, v219
	v_cvt_pk_fp8_f32 v250, v179, v254 op_sel:[0,0,1]
	s_waitcnt lgkmcnt(2)
	v_mfma_scale_f32_32x32x64_f8f6f4 v[66:81], v[222:229], v[138:145], v[66:81], v194, v193 op_sel_hi:[0,0,0]
	ds_read_b128 v[222:225], v185 offset:34816
	ds_read_b128 v[226:229], v186 offset:34816
	v_exp_f32_e32 v0, v102
	v_exp_f32_e32 v177, v103
	v_exp_f32_e32 v179, v104
	v_exp_f32_e32 v254, v105
	v_add_f32_e32 v219, v0, v219
	v_add_f32_e32 v219, v177, v219
	v_cvt_pk_fp8_f32 v251, v0, v177
	v_add_f32_e32 v219, v179, v219
	v_add_f32_e32 v219, v254, v219
	v_cvt_pk_fp8_f32 v251, v179, v254 op_sel:[0,0,1]
	v_exp_f32_e32 v0, v106
	v_exp_f32_e32 v177, v107
	v_exp_f32_e32 v179, v108
	v_exp_f32_e32 v254, v109
	v_add_f32_e32 v219, v0, v219
	v_add_f32_e32 v219, v177, v219
	v_cvt_pk_fp8_f32 v252, v0, v177
	v_add_f32_e32 v219, v179, v219
	v_add_f32_e32 v219, v254, v219
	v_cvt_pk_fp8_f32 v252, v179, v254 op_sel:[0,0,1]
	s_waitcnt lgkmcnt(2)
	v_mfma_scale_f32_32x32x64_f8f6f4 v[82:97], v[122:129], v[130:137], v[82:97], v194, v193 op_sel_hi:[0,0,0]
	v_exp_f32_e32 v0, v110
	v_exp_f32_e32 v177, v111
	v_exp_f32_e32 v179, v112
	v_exp_f32_e32 v254, v113
	v_add_f32_e32 v219, v0, v219
	v_add_f32_e32 v219, v177, v219
	v_cvt_pk_fp8_f32 v253, v0, v177
	v_add_f32_e32 v219, v179, v219
	v_add_f32_e32 v219, v254, v219
	v_cvt_pk_fp8_f32 v253, v179, v254 op_sel:[0,0,1]
	ds_read_b128 v[122:125], v170 offset:8192
	ds_read_b128 v[126:129], v171 offset:8192
	ds_read_b128 v[114:117], v170 offset:10240
	ds_read_b128 v[118:121], v171 offset:10240
	ds_read_b128 v[106:109], v170 offset:12288
	ds_read_b128 v[110:113], v171 offset:12288
	ds_read_b128 v[98:101], v170 offset:14336
	ds_read_b128 v[102:105], v171 offset:14336
	s_waitcnt lgkmcnt(8)
	v_mfma_scale_f32_32x32x64_f8f6f4 v[66:81], v[222:229], v[130:137], v[66:81], v194, v193 op_sel_hi:[0,0,0]
	v_mov_b32_e32 v0, v219
	s_nop 1
	v_permlane32_swap_b32_e32 v219, v0
	v_add_f32_e32 v219, v219, v0
	v_fma_f32 v209, v209, v221, v219
	v_max_f32_e32 v177, v82, v83
	v_max3_f32 v177, v177, v84, v85
	v_max3_f32 v177, v177, v86, v87
	v_max3_f32 v177, v177, v88, v89
	v_max3_f32 v177, v177, v90, v91
	v_max3_f32 v177, v177, v92, v93
	v_max3_f32 v177, v177, v94, v95
	v_max3_f32 v177, v177, v96, v97
	s_waitcnt lgkmcnt(6)
	v_mfma_scale_f32_32x32x64_f8f6f4 v[50:65], v[246:253], v[122:129], v[50:65], v194, v194 op_sel_hi:[0,0,0]
	s_waitcnt lgkmcnt(4)
	v_mfma_scale_f32_32x32x64_f8f6f4 v[34:49], v[246:253], v[114:121], v[34:49], v194, v194 op_sel_hi:[0,0,0]
	s_waitcnt lgkmcnt(2)
	v_mfma_scale_f32_32x32x64_f8f6f4 v[18:33], v[246:253], v[106:113], v[18:33], v194, v194 op_sel_hi:[0,0,0]
	s_waitcnt lgkmcnt(0)
	v_mfma_scale_f32_32x32x64_f8f6f4 v[2:17], v[246:253], v[98:105], v[2:17], v194, v194 op_sel_hi:[0,0,0]
	s_waitcnt vmcnt(3)
	s_waitcnt lgkmcnt(0)
	s_barrier
	v_max_f32_e32 v0, v66, v67
	v_max3_f32 v0, v0, v68, v69
	v_max3_f32 v0, v0, v70, v71
	v_max3_f32 v0, v0, v72, v73
	v_max3_f32 v0, v0, v74, v75
	v_max3_f32 v0, v0, v76, v77
	v_max3_f32 v0, v0, v78, v79
	v_max3_f32 v0, v0, v80, v81
	v_max_f32_e32 v177, v177, v0
	v_mov_b32_e32 v0, v177
	v_mov_b32_e32 v218, 1.0
	s_nop 0
	v_permlane32_swap_b32_e32 v177, v0
	v_max_f32_e32 v177, v177, v0
	v_cmp_ge_f32_e32 vcc, s90, v177
	s_cmp_eq_u64 vcc, exec
	s_cbranch_scc0 .Lmla_h3_newmax
.Lmla_h3_cont:
	s_add_i32 s30, s30, 1
	s_cmpk_lt_u32 s30, 63
	s_cbranch_scc1 .LBB0_1321
	ds_read_b128 v[114:117], v215 offset:24576
	ds_read_b128 v[118:121], v216 offset:24576
	ds_read_b128 v[222:225], v215 offset:28672
	ds_read_b128 v[226:229], v216 offset:28672
	s_add_i32 m0, s98, 0xc800
	s_nop 0
	global_load_lds_dwordx4 v176, s[18:19]
	s_add_i32 m0, s98, 0x10800
	s_nop 0
	global_load_lds_dwordx4 v178, s[16:17]
	s_add_i32 m0, s98, 0x13800
	s_nop 0
	global_load_lds_dwordx4 v[180:181], off
	v_add_u32_e32 v176, 0x2000, v176
	v_add_u32_e32 v178, 0x20000, v178
	s_mov_b64 s[20:21], 0x1000
	v_lshl_add_u64 v[180:181], v[180:181], 0, s[20:21]
	v_exp_f32_e32 v0, v82
	v_exp_f32_e32 v177, v83
	v_exp_f32_e32 v179, v84
	v_exp_f32_e32 v254, v85
	v_add_f32_e32 v219, v0, v177
	v_cvt_pk_fp8_f32 v246, v0, v177
	v_add_f32_e32 v219, v179, v219
	v_add_f32_e32 v219, v254, v219
	v_cvt_pk_fp8_f32 v246, v179, v254 op_sel:[0,0,1]
	s_waitcnt lgkmcnt(2)
	v_mfma_scale_f32_32x32x64_f8f6f4 v[114:129], v[114:121], v[146:153], v[230:245], v194, v193 op_sel_hi:[0,0,0]
	v_exp_f32_e32 v0, v86
	v_exp_f32_e32 v177, v87
	v_exp_f32_e32 v179, v88
	v_exp_f32_e32 v254, v89
	v_add_f32_e32 v219, v0, v219
	v_add_f32_e32 v219, v177, v219
	v_cvt_pk_fp8_f32 v247, v0, v177
	v_add_f32_e32 v219, v179, v219
	v_add_f32_e32 v219, v254, v219
	v_cvt_pk_fp8_f32 v247, v179, v254 op_sel:[0,0,1]
	ds_read_b128 v[82:85], v213 offset:24576
	ds_read_b128 v[86:89], v214 offset:24576
	s_waitcnt lgkmcnt(2)
	v_mfma_scale_f32_32x32x64_f8f6f4 v[98:113], v[222:229], v[146:153], v[230:245], v194, v193 op_sel_hi:[0,0,0]
	ds_read_b128 v[222:225], v213 offset:28672
	ds_read_b128 v[226:229], v214 offset:28672
	v_exp_f32_e32 v0, v90
	v_exp_f32_e32 v177, v91
	v_exp_f32_e32 v179, v92
	v_exp_f32_e32 v254, v93
	v_add_f32_e32 v219, v0, v219
	v_add_f32_e32 v219, v177, v219
	v_cvt_pk_fp8_f32 v248, v0, v177
	v_add_f32_e32 v219, v179, v219
	v_add_f32_e32 v219, v254, v219
	v_cvt_pk_fp8_f32 v248, v179, v254 op_sel:[0,0,1]
	v_exp_f32_e32 v0, v94
	v_exp_f32_e32 v177, v95
	v_exp_f32_e32 v179, v96
	v_exp_f32_e32 v254, v97
	v_add_f32_e32 v219, v0, v219
	v_add_f32_e32 v219, v177, v219
	v_cvt_pk_fp8_f32 v249, v0, v177
	v_add_f32_e32 v219, v179, v219
	v_add_f32_e32 v219, v254, v219
	v_cvt_pk_fp8_f32 v249, v179, v254 op_sel:[0,0,1]
	ds_read_b128 v[90:93], v185 offset:36864
	ds_read_b128 v[94:97], v186 offset:36864
	s_waitcnt lgkmcnt(4)
; __device__ __forceinline__ void finishSM9(f32x16& p0, f32x16& p1, float alpha, float& l_reg, v8i32& p8) {
; #pragma unroll
;   for (int r = 0; r < 16; ++r) { p0[r] = __builtin_amdgcn_exp2f(p0[r]); p1[r] = __builtin_amdgcn_exp2f(p1[r]); }
;   float ps = 0;
; #pragma unroll
;   for (int r = 0; r < 16; ++r) ps += p0[r];
; #pragma unroll
;   for (int r = 0; r < 16; ++r) ps += p1[r];
;   { auto rr = __builtin_amdgcn_permlane32_swap(__float_as_uint(ps), __float_as_uint(ps), false, false);
;     ps = __uint_as_float(rr[0]) + __uint_as_float(rr[1]); }
;   l_reg = l_reg * alpha + ps;
; #pragma unroll
;   for (int g = 0; g < 4; ++g) {
;     int w = __builtin_amdgcn_cvt_pk_fp8_f32(p0[4 * g], p0[4 * g + 1], 0, false); p8[g] = __builtin_amdgcn_cvt_pk_fp8_f32(p0[4 * g + 2], p0[4 * g + 3], w, true);
;     int u = __builtin_amdgcn_cvt_pk_fp8_f32(p1[4 * g], p1[4 * g + 1], 0, false); p8[4 + g] = __builtin_amdgcn_cvt_pk_fp8_f32(p1[4 * g + 2], p1[4 * g + 3], u, true); }
; }
; __device__ __forceinline__ void pv8(f32x16* o, const char* Vt, const v8i32 p8, int r32, int hi) {
;   const int sw = (r32 >> 2) & 3, a0 = r32 * 64 + (((hi * 2) ^ sw) << 4), a1 = r32 * 64 + (((hi * 2 + 1) ^ sw) << 4);
; #pragma unroll
;   for (int d0 = 0; d0 < 4; ++d0) {
;     const v8i32 vf = cat8(*reinterpret_cast<const v4i32*>(Vt + d0 * 2048 + a0), *reinterpret_cast<const v4i32*>(Vt + d0 * 2048 + a1));
;     o[d0] = __builtin_amdgcn_mfma_scale_f32_32x32x64_f8f6f4(p8, vf, o[d0], 0, 0, 0, 127, 0, 127); }
; }
; __device__ __forceinline__ void qkt9(f32x16& p0, f32x16& p1, const char* Kn, const char* Kr, const v8i32* qf, const float init, int r32, int hi) {
; #pragma unroll
;   for (int r = 0; r < 16; ++r) { p0[r] = init; p1[r] = init; }
; #pragma unroll
;   for (int s = 0; s < 2; ++s) { const int c0 = s * 4 + hi * 2;
;     const v8i32 a0 = cat8(*reinterpret_cast<const v4i32*>(Kn + KN8SW(r32, c0)), *reinterpret_cast<const v4i32*>(Kn + KN8SW(r32, c0 + 1)));
;     const v8i32 a1 = cat8(*reinterpret_cast<const v4i32*>(Kn + 4096 + KN8SW(r32, c0)), *reinterpret_cast<const v4i32*>(Kn + 4096 + KN8SW(r32, c0 + 1)));
;     p0 = __builtin_amdgcn_mfma_scale_f32_32x32x64_f8f6f4(a0, qf[s], p0, 0, 0, 0, 127, 0, 124);
;     p1 = __builtin_amdgcn_mfma_scale_f32_32x32x64_f8f6f4(a1, qf[s], p1, 0, 0, 0, 127, 0, 124); }
;   { const int c0 = hi * 2;
	v_mfma_scale_f32_32x32x64_f8f6f4 v[114:129], v[82:89], v[138:145], v[114:129], v194, v193 op_sel_hi:[0,0,0]
	v_exp_f32_e32 v0, v66
	v_exp_f32_e32 v177, v67
	v_exp_f32_e32 v179, v68
	v_exp_f32_e32 v254, v69
	v_add_f32_e32 v219, v0, v219
	v_add_f32_e32 v219, v177, v219
	v_cvt_pk_fp8_f32 v250, v0, v177
	v_add_f32_e32 v219, v179, v219
	v_add_f32_e32 v219, v254, v219
	v_cvt_pk_fp8_f32 v250, v179, v254 op_sel:[0,0,1]
	s_waitcnt lgkmcnt(2)
	v_mfma_scale_f32_32x32x64_f8f6f4 v[98:113], v[222:229], v[138:145], v[98:113], v194, v193 op_sel_hi:[0,0,0]
	ds_read_b128 v[222:225], v185 offset:38912
	ds_read_b128 v[226:229], v186 offset:38912
	v_exp_f32_e32 v0, v70
	v_exp_f32_e32 v177, v71
	v_exp_f32_e32 v179, v72
	v_exp_f32_e32 v254, v73
	v_add_f32_e32 v219, v0, v219
	v_add_f32_e32 v219, v177, v219
	v_cvt_pk_fp8_f32 v251, v0, v177
	v_add_f32_e32 v219, v179, v219
	v_add_f32_e32 v219, v254, v219
	v_cvt_pk_fp8_f32 v251, v179, v254 op_sel:[0,0,1]
	v_exp_f32_e32 v0, v74
	v_exp_f32_e32 v177, v75
	v_exp_f32_e32 v179, v76
	v_exp_f32_e32 v254, v77
	v_add_f32_e32 v219, v0, v219
	v_add_f32_e32 v219, v177, v219
	v_cvt_pk_fp8_f32 v252, v0, v177
	v_add_f32_e32 v219, v179, v219
	v_add_f32_e32 v219, v254, v219
	v_cvt_pk_fp8_f32 v252, v179, v254 op_sel:[0,0,1]
	s_waitcnt lgkmcnt(2)
	v_mfma_scale_f32_32x32x64_f8f6f4 v[114:129], v[90:97], v[130:137], v[114:129], v194, v193 op_sel_hi:[0,0,0]
	v_exp_f32_e32 v0, v78
	v_exp_f32_e32 v177, v79
	v_exp_f32_e32 v179, v80
	v_exp_f32_e32 v254, v81
	v_add_f32_e32 v219, v0, v219
	v_add_f32_e32 v219, v177, v219
	v_cvt_pk_fp8_f32 v253, v0, v177
	v_add_f32_e32 v219, v179, v219
	v_add_f32_e32 v219, v254, v219
	v_cvt_pk_fp8_f32 v253, v179, v254 op_sel:[0,0,1]
	ds_read_b128 v[90:93], v185 offset:0
	ds_read_b128 v[94:97], v186 offset:0
	ds_read_b128 v[82:85], v185 offset:2048
	ds_read_b128 v[86:89], v186 offset:2048
	ds_read_b128 v[74:77], v185 offset:4096
	ds_read_b128 v[78:81], v186 offset:4096
	ds_read_b128 v[66:69], v185 offset:6144
	ds_read_b128 v[70:73], v186 offset:6144
	s_waitcnt lgkmcnt(8)
	v_mfma_scale_f32_32x32x64_f8f6f4 v[98:113], v[222:229], v[130:137], v[98:113], v194, v193 op_sel_hi:[0,0,0]
	v_mov_b32_e32 v0, v219
	s_nop 1
	v_permlane32_swap_b32_e32 v219, v0
	v_add_f32_e32 v219, v219, v0
	v_fma_f32 v209, v209, v218, v219
	v_max_f32_e32 v177, v114, v115
	v_max3_f32 v177, v177, v116, v117
	v_max3_f32 v177, v177, v118, v119
	v_max3_f32 v177, v177, v120, v121
	v_max3_f32 v177, v177, v122, v123
	v_max3_f32 v177, v177, v124, v125
	v_max3_f32 v177, v177, v126, v127
	v_max3_f32 v177, v177, v128, v129
	s_waitcnt lgkmcnt(6)
	v_mfma_scale_f32_32x32x64_f8f6f4 v[50:65], v[246:253], v[90:97], v[50:65], v194, v194 op_sel_hi:[0,0,0]
	s_waitcnt lgkmcnt(4)
	v_mfma_scale_f32_32x32x64_f8f6f4 v[34:49], v[246:253], v[82:89], v[34:49], v194, v194 op_sel_hi:[0,0,0]
	s_waitcnt lgkmcnt(2)
	v_mfma_scale_f32_32x32x64_f8f6f4 v[18:33], v[246:253], v[74:81], v[18:33], v194, v194 op_sel_hi:[0,0,0]
	s_waitcnt lgkmcnt(0)
	v_mfma_scale_f32_32x32x64_f8f6f4 v[2:17], v[246:253], v[66:73], v[2:17], v194, v194 op_sel_hi:[0,0,0]
	s_waitcnt vmcnt(3)
	s_waitcnt lgkmcnt(0)
	s_barrier
	v_max_f32_e32 v0, v98, v99
	v_max3_f32 v0, v0, v100, v101
	v_max3_f32 v0, v0, v102, v103
	v_max3_f32 v0, v0, v104, v105
	v_max3_f32 v0, v0, v106, v107
	v_max3_f32 v0, v0, v108, v109
	v_max3_f32 v0, v0, v110, v111
	v_max3_f32 v0, v0, v112, v113
	v_max_f32_e32 v177, v177, v0
	v_mov_b32_e32 v0, v177
	v_mov_b32_e32 v221, 1.0
	s_nop 0
	v_permlane32_swap_b32_e32 v177, v0
	v_max_f32_e32 v177, v177, v0
	v_cmp_ge_f32_e32 vcc, s90, v177
	s_cmp_eq_u64 vcc, exec
	s_cbranch_scc0 .Lmla_p0_newmax
; __device__ __forceinline__ void finishSM9(f32x16& p0, f32x16& p1, float alpha, float& l_reg, v8i32& p8) {
; #pragma unroll
;   for (int r = 0; r < 16; ++r) { p0[r] = __builtin_amdgcn_exp2f(p0[r]); p1[r] = __builtin_amdgcn_exp2f(p1[r]); }
;   float ps = 0;
; #pragma unroll
;   for (int r = 0; r < 16; ++r) ps += p0[r];
; #pragma unroll
;   for (int r = 0; r < 16; ++r) ps += p1[r];
;   { auto rr = __builtin_amdgcn_permlane32_swap(__float_as_uint(ps), __float_as_uint(ps), false, false);
;     ps = __uint_as_float(rr[0]) + __uint_as_float(rr[1]); }
;   l_reg = l_reg * alpha + ps;
; #pragma unroll
;   for (int g = 0; g < 4; ++g) {
;     int w = __builtin_amdgcn_cvt_pk_fp8_f32(p0[4 * g], p0[4 * g + 1], 0, false); p8[g] = __builtin_amdgcn_cvt_pk_fp8_f32(p0[4 * g + 2], p0[4 * g + 3], w, true);
;     int u = __builtin_amdgcn_cvt_pk_fp8_f32(p1[4 * g], p1[4 * g + 1], 0, false); p8[4 + g] = __builtin_amdgcn_cvt_pk_fp8_f32(p1[4 * g + 2], p1[4 * g + 3], u, true); }
; }
; __device__ __forceinline__ void pv8(f32x16* o, const char* Vt, const v8i32 p8, int r32, int hi) {
;   const int sw = (r32 >> 2) & 3, a0 = r32 * 64 + (((hi * 2) ^ sw) << 4), a1 = r32 * 64 + (((hi * 2 + 1) ^ sw) << 4);
; #pragma unroll
;   for (int d0 = 0; d0 < 4; ++d0) {
;     const v8i32 vf = cat8(*reinterpret_cast<const v4i32*>(Vt + d0 * 2048 + a0), *reinterpret_cast<const v4i32*>(Vt + d0 * 2048 + a1));
;     o[d0] = __builtin_amdgcn_mfma_scale_f32_32x32x64_f8f6f4(p8, vf, o[d0], 0, 0, 0, 127, 0, 127); }
; }
; __device__ __forceinline__ void qkt9(f32x16& p0, f32x16& p1, const char* Kn, const char* Kr, const v8i32* qf, const float init, int r32, int hi) {
; #pragma unroll
;   for (int r = 0; r < 16; ++r) { p0[r] = init; p1[r] = init; }
; #pragma unroll
;   for (int s = 0; s < 2; ++s) { const int c0 = s * 4 + hi * 2;
;     const v8i32 a0 = cat8(*reinterpret_cast<const v4i32*>(Kn + KN8SW(r32, c0)), *reinterpret_cast<const v4i32*>(Kn + KN8SW(r32, c0 + 1)));
;     const v8i32 a1 = cat8(*reinterpret_cast<const v4i32*>(Kn + 4096 + KN8SW(r32, c0)), *reinterpret_cast<const v4i32*>(Kn + 4096 + KN8SW(r32, c0 + 1)));
;     p0 = __builtin_amdgcn_mfma_scale_f32_32x32x64_f8f6f4(a0, qf[s], p0, 0, 0, 0, 127, 0, 124);
;     p1 = __builtin_amdgcn_mfma_scale_f32_32x32x64_f8f6f4(a1, qf[s], p1, 0, 0, 0, 127, 0, 124); }
;   { const int c0 = hi * 2;
.Lmla_p0_cont:
	ds_read_b128 v[82:85], v166 offset:16384
	ds_read_b128 v[86:89], v167 offset:16384
	ds_read_b128 v[222:225], v166 offset:20480
	ds_read_b128 v[226:229], v167 offset:20480
	v_add_u32_e32 v176, 0x2000, v176
	v_add_u32_e32 v178, 0x20000, v178
	s_mov_b64 s[20:21], 0x1000
	v_lshl_add_u64 v[180:181], v[180:181], 0, s[20:21]
	v_exp_f32_e32 v0, v114
	v_exp_f32_e32 v177, v115
	v_exp_f32_e32 v179, v116
	v_exp_f32_e32 v254, v117
	v_add_f32_e32 v219, v0, v177
	v_cvt_pk_fp8_f32 v246, v0, v177
	v_add_f32_e32 v219, v179, v219
	v_add_f32_e32 v219, v254, v219
	v_cvt_pk_fp8_f32 v246, v179, v254 op_sel:[0,0,1]
	s_waitcnt lgkmcnt(2)
	v_mfma_scale_f32_32x32x64_f8f6f4 v[82:97], v[82:89], v[146:153], v[230:245], v194, v193 op_sel_hi:[0,0,0]
	v_exp_f32_e32 v0, v118
	v_exp_f32_e32 v177, v119
	v_exp_f32_e32 v179, v120
	v_exp_f32_e32 v254, v121
	v_add_f32_e32 v219, v0, v219
	v_add_f32_e32 v219, v177, v219
	v_cvt_pk_fp8_f32 v247, v0, v177
	v_add_f32_e32 v219, v179, v219
	v_add_f32_e32 v219, v254, v219
	v_cvt_pk_fp8_f32 v247, v179, v254 op_sel:[0,0,1]
	ds_read_b128 v[114:117], v168 offset:16384
	ds_read_b128 v[118:121], v169 offset:16384
	s_waitcnt lgkmcnt(2)
	v_mfma_scale_f32_32x32x64_f8f6f4 v[66:81], v[222:229], v[146:153], v[230:245], v194, v193 op_sel_hi:[0,0,0]
	ds_read_b128 v[222:225], v168 offset:20480
	ds_read_b128 v[226:229], v169 offset:20480
	v_exp_f32_e32 v0, v122
	v_exp_f32_e32 v177, v123
	v_exp_f32_e32 v179, v124
	v_exp_f32_e32 v254, v125
	v_add_f32_e32 v219, v0, v219
	v_add_f32_e32 v219, v177, v219
	v_cvt_pk_fp8_f32 v248, v0, v177
	v_add_f32_e32 v219, v179, v219
	v_add_f32_e32 v219, v254, v219
	v_cvt_pk_fp8_f32 v248, v179, v254 op_sel:[0,0,1]
	v_exp_f32_e32 v0, v126
	v_exp_f32_e32 v177, v127
	v_exp_f32_e32 v179, v128
	v_exp_f32_e32 v254, v129
	v_add_f32_e32 v219, v0, v219
	v_add_f32_e32 v219, v177, v219
	v_cvt_pk_fp8_f32 v249, v0, v177
	v_add_f32_e32 v219, v179, v219
	v_add_f32_e32 v219, v254, v219
	v_cvt_pk_fp8_f32 v249, v179, v254 op_sel:[0,0,1]
	ds_read_b128 v[122:125], v170 offset:32768
	ds_read_b128 v[126:129], v171 offset:32768
	s_waitcnt lgkmcnt(4)
	v_mfma_scale_f32_32x32x64_f8f6f4 v[82:97], v[114:121], v[138:145], v[82:97], v194, v193 op_sel_hi:[0,0,0]
	v_exp_f32_e32 v0, v98
	v_exp_f32_e32 v177, v99
	v_exp_f32_e32 v179, v100
	v_exp_f32_e32 v254, v101
	v_add_f32_e32 v219, v0, v219
	v_add_f32_e32 v219, v177, v219
	v_cvt_pk_fp8_f32 v250, v0, v177
	v_add_f32_e32 v219, v179, v219
	v_add_f32_e32 v219, v254, v219
	v_cvt_pk_fp8_f32 v250, v179, v254 op_sel:[0,0,1]
	s_waitcnt lgkmcnt(2)
	v_mfma_scale_f32_32x32x64_f8f6f4 v[66:81], v[222:229], v[138:145], v[66:81], v194, v193 op_sel_hi:[0,0,0]
	ds_read_b128 v[222:225], v170 offset:34816
	ds_read_b128 v[226:229], v171 offset:34816
	v_exp_f32_e32 v0, v102
	v_exp_f32_e32 v177, v103
	v_exp_f32_e32 v179, v104
	v_exp_f32_e32 v254, v105
	v_add_f32_e32 v219, v0, v219
	v_add_f32_e32 v219, v177, v219
	v_cvt_pk_fp8_f32 v251, v0, v177
	v_add_f32_e32 v219, v179, v219
	v_add_f32_e32 v219, v254, v219
	v_cvt_pk_fp8_f32 v251, v179, v254 op_sel:[0,0,1]
	v_exp_f32_e32 v0, v106
	v_exp_f32_e32 v177, v107
	v_exp_f32_e32 v179, v108
	v_exp_f32_e32 v254, v109
	v_add_f32_e32 v219, v0, v219
	v_add_f32_e32 v219, v177, v219
	v_cvt_pk_fp8_f32 v252, v0, v177
	v_add_f32_e32 v219, v179, v219
	v_add_f32_e32 v219, v254, v219
	v_cvt_pk_fp8_f32 v252, v179, v254 op_sel:[0,0,1]
	s_waitcnt lgkmcnt(2)
	v_mfma_scale_f32_32x32x64_f8f6f4 v[82:97], v[122:129], v[130:137], v[82:97], v194, v193 op_sel_hi:[0,0,0]
	v_exp_f32_e32 v0, v110
	v_exp_f32_e32 v177, v111
	v_exp_f32_e32 v179, v112
	v_exp_f32_e32 v254, v113
	v_add_f32_e32 v219, v0, v219
	v_add_f32_e32 v219, v177, v219
	v_cvt_pk_fp8_f32 v253, v0, v177
	v_add_f32_e32 v219, v179, v219
	v_add_f32_e32 v219, v254, v219
	v_cvt_pk_fp8_f32 v253, v179, v254 op_sel:[0,0,1]
	ds_read_b128 v[122:125], v185 offset:8192
	ds_read_b128 v[126:129], v186 offset:8192
	ds_read_b128 v[114:117], v185 offset:10240
	ds_read_b128 v[118:121], v186 offset:10240
	ds_read_b128 v[106:109], v185 offset:12288
	ds_read_b128 v[110:113], v186 offset:12288
	ds_read_b128 v[98:101], v185 offset:14336
	ds_read_b128 v[102:105], v186 offset:14336
	s_waitcnt lgkmcnt(8)
	v_mfma_scale_f32_32x32x64_f8f6f4 v[66:81], v[222:229], v[130:137], v[66:81], v194, v193 op_sel_hi:[0,0,0]
	v_mov_b32_e32 v0, v219
	s_nop 1
	v_permlane32_swap_b32_e32 v219, v0
	v_add_f32_e32 v219, v219, v0
	v_fma_f32 v209, v209, v221, v219
	v_max_f32_e32 v177, v82, v83
	v_max3_f32 v177, v177, v84, v85
	v_max3_f32 v177, v177, v86, v87
	v_max3_f32 v177, v177, v88, v89
	v_max3_f32 v177, v177, v90, v91
	v_max3_f32 v177, v177, v92, v93
	v_max3_f32 v177, v177, v94, v95
	v_max3_f32 v177, v177, v96, v97
	s_waitcnt lgkmcnt(6)
	v_mfma_scale_f32_32x32x64_f8f6f4 v[50:65], v[246:253], v[122:129], v[50:65], v194, v194 op_sel_hi:[0,0,0]
	s_waitcnt lgkmcnt(4)
	v_mfma_scale_f32_32x32x64_f8f6f4 v[34:49], v[246:253], v[114:121], v[34:49], v194, v194 op_sel_hi:[0,0,0]
	s_waitcnt lgkmcnt(2)
	v_mfma_scale_f32_32x32x64_f8f6f4 v[18:33], v[246:253], v[106:113], v[18:33], v194, v194 op_sel_hi:[0,0,0]
	s_waitcnt lgkmcnt(0)
	v_mfma_scale_f32_32x32x64_f8f6f4 v[2:17], v[246:253], v[98:105], v[2:17], v194, v194 op_sel_hi:[0,0,0]
	s_waitcnt vmcnt(0)
	s_waitcnt lgkmcnt(0)
	s_barrier
	v_max_f32_e32 v0, v66, v67
	v_max3_f32 v0, v0, v68, v69
	v_max3_f32 v0, v0, v70, v71
	v_max3_f32 v0, v0, v72, v73
	v_max3_f32 v0, v0, v74, v75
	v_max3_f32 v0, v0, v76, v77
	v_max3_f32 v0, v0, v78, v79
	v_max3_f32 v0, v0, v80, v81
	v_max_f32_e32 v177, v177, v0
	v_mov_b32_e32 v0, v177
	v_mov_b32_e32 v218, 1.0
	s_nop 0
	v_permlane32_swap_b32_e32 v177, v0
	v_max_f32_e32 v177, v177, v0
	v_cmp_ge_f32_e32 vcc, s90, v177
	s_cmp_eq_u64 vcc, exec
	s_cbranch_scc0 .Lmla_p1_newmax

; #define SLOAD() do { vs0 = *(const bf16x8*)(Vh + voff); vs1 = *(const bf16x8*)(Vh + voff + 32u * (unsigned)ldv); \
;     ks0 = *(const bf16x8*)(Kh + koff); ks1 = *(const bf16x8*)(Kh + koff + 32u * (unsigned)ldk); \
;     if constexpr (NR > 0) { kr = *(const bf16x8*)(Krh + kroff); kroff += 64u * 64u; } voff += 64u * (unsigned)ldv; koff += 64u * (unsigned)ldk; } while (0)
; #define SWRITE(b) do { *(bf16x8*)(V_lds + (b) * SHM_V + vst0) = vs0; *(bf16x8*)(V_lds + (b) * SHM_V + vst1) = vs1; const int kc = sc * 2;  \
;     *(bf16x8*)(K_lds + (b) * SHM_K + KSWZ(sr, kc)) = ks0; *(bf16x8*)(K_lds + (b) * SHM_K + KSWZ(32 + sr, kc)) = ks1; \
;     if constexpr (NR > 0) *(bf16x8*)(Kr_lds + (b) * SHM_KR + krst) = kr; } while (0)
; __device__ __forceinline__ void pv8(f32x16* o, const char* Vt, const v8i32 p8, int r32, int hi) {
;   const int sw = (r32 >> 2) & 3, a0 = r32 * 64 + (((hi * 2) ^ sw) << 4), a1 = r32 * 64 + (((hi * 2 + 1) ^ sw) << 4);
; #pragma unroll
;   for (int d0 = 0; d0 < 4; ++d0) {
;     const v8i32 vf = cat8(*reinterpret_cast<const v4i32*>(Vt + d0 * 2048 + a0), *reinterpret_cast<const v4i32*>(Vt + d0 * 2048 + a1));
;     o[d0] = __builtin_amdgcn_mfma_scale_f32_32x32x64_f8f6f4(p8, vf, o[d0], 0, 0, 0, 127, 0, 127); }
; }
; __device__ __forceinline__ void attn_unit7(const unsigned char* __restrict__ Q8, int ldq, const unsigned char* __restrict__ Kn8, int ldk, const unsigned char* __restrict__ Kr8, ...
;     ...
;   f32x16 pA0, pA1, pB0, pB1; float alA, alB; v8i32 p8;
;   SLOAD(); SWRITE(0); __syncthreads();
;   SLOAD();
;   qkt9(pA0, pA1, Kn_lds, Kr_lds, qf, 7.0f - m_reg, r32, hi); partialSM9(pA0, pA1, m_reg, alA, thr_raw);
;   SWRITE(1); __syncthreads();
;   for (int j = 1; j + 1 < NT; j += 2) {
;     SLOAD();
;     qkt9(pB0, pB1, Kn_lds + 8192, Kr_lds + 4096, qf, 7.0f - m_reg, r32, hi);
;     finishSM9(pA0, pA1, alA, l_reg, p8);
;     pv8(o, Vt_lds, p8, r32, hi); partialSM9(pB0, pB1, m_reg, alB, thr_raw);
;     __syncthreads(); SWRITE(0);
;     RESC(alB); __syncthreads();
;     if (j + 2 < NT) SLOAD();
;     qkt9(pA0, pA1, Kn_lds, Kr_lds, qf, 7.0f - m_reg, r32, hi);
;     finishSM9(pB0, pB1, alB, l_reg, p8);
;     pv8(o, Vt_lds + 8192, p8, r32, hi); partialSM9(pA0, pA1, m_reg, alA, thr_raw);
;     __syncthreads(); if (j + 2 < NT) SWRITE(1);
;     RESC(alA); __syncthreads();
;   }
.Lmla_stag_entry:
	s_add_i32 m0, s98, 0xa800
	s_nop 0
	global_load_lds_dwordx4 v176, s[18:19]
	s_add_i32 m0, s98, 0xe800
	s_nop 0
	global_load_lds_dwordx4 v178, s[16:17]
	v_add_u32_e32 v176, 0x2000, v176
	v_add_u32_e32 v178, 0x20000, v178
	s_add_i32 m0, s98, 0xc800
	s_nop 0
	global_load_lds_dwordx4 v176, s[18:19]
	s_add_i32 m0, s98, 0x10800
	s_nop 0
	global_load_lds_dwordx4 v178, s[16:17]
	s_nop 1
	v_add_u32_e32 v176, 0x2000, v176
	v_add_u32_e32 v178, 0x20000, v178
.Lmla_stag_loop:
	ds_read_b128 v[114:117], v215 offset:24576
	ds_read_b128 v[118:121], v216 offset:24576
	ds_read_b128 v[222:225], v215 offset:28672
	ds_read_b128 v[226:229], v216 offset:28672
	v_exp_f32_e32 v0, v82
	v_exp_f32_e32 v177, v83
	v_exp_f32_e32 v179, v84
	v_exp_f32_e32 v254, v85
	v_add_f32_e32 v219, v0, v177
	v_cvt_pk_fp8_f32 v246, v0, v177
	v_add_f32_e32 v219, v179, v219
	v_add_f32_e32 v219, v254, v219
	v_cvt_pk_fp8_f32 v246, v179, v254 op_sel:[0,0,1]
	s_waitcnt lgkmcnt(2)
	v_mfma_scale_f32_32x32x64_f8f6f4 v[114:129], v[114:121], v[146:153], v[230:245], v194, v193 op_sel_hi:[0,0,0]
	v_exp_f32_e32 v0, v86
	v_exp_f32_e32 v177, v87
	v_exp_f32_e32 v179, v88
	v_exp_f32_e32 v254, v89
	v_add_f32_e32 v219, v0, v219
	v_add_f32_e32 v219, v177, v219
	v_cvt_pk_fp8_f32 v247, v0, v177
	v_add_f32_e32 v219, v179, v219
	v_add_f32_e32 v219, v254, v219
	v_cvt_pk_fp8_f32 v247, v179, v254 op_sel:[0,0,1]
	ds_read_b128 v[82:85], v213 offset:24576
	ds_read_b128 v[86:89], v214 offset:24576
	s_waitcnt lgkmcnt(2)
	v_mfma_scale_f32_32x32x64_f8f6f4 v[98:113], v[222:229], v[146:153], v[230:245], v194, v193 op_sel_hi:[0,0,0]
	ds_read_b128 v[222:225], v213 offset:28672
	ds_read_b128 v[226:229], v214 offset:28672
	v_exp_f32_e32 v0, v90
	v_exp_f32_e32 v177, v91
	v_exp_f32_e32 v179, v92
	v_exp_f32_e32 v254, v93
	v_add_f32_e32 v219, v0, v219
	v_add_f32_e32 v219, v177, v219
	v_cvt_pk_fp8_f32 v248, v0, v177
	v_add_f32_e32 v219, v179, v219
	v_add_f32_e32 v219, v254, v219
	v_cvt_pk_fp8_f32 v248, v179, v254 op_sel:[0,0,1]
	v_exp_f32_e32 v0, v94
	v_exp_f32_e32 v177, v95
	v_exp_f32_e32 v179, v96
	v_exp_f32_e32 v254, v97
	v_add_f32_e32 v219, v0, v219
	v_add_f32_e32 v219, v177, v219
	v_cvt_pk_fp8_f32 v249, v0, v177
	v_add_f32_e32 v219, v179, v219
	v_add_f32_e32 v219, v254, v219
	v_cvt_pk_fp8_f32 v249, v179, v254 op_sel:[0,0,1]
	ds_read_b128 v[90:93], v185 offset:36864
	ds_read_b128 v[94:97], v186 offset:36864
	s_waitcnt lgkmcnt(4)
	v_mfma_scale_f32_32x32x64_f8f6f4 v[114:129], v[82:89], v[138:145], v[114:129], v194, v193 op_sel_hi:[0,0,0]
	v_exp_f32_e32 v0, v66
	v_exp_f32_e32 v177, v67
	v_exp_f32_e32 v179, v68
	v_exp_f32_e32 v254, v69
	v_add_f32_e32 v219, v0, v219
	v_add_f32_e32 v219, v177, v219
	v_cvt_pk_fp8_f32 v250, v0, v177
	v_add_f32_e32 v219, v179, v219
	v_add_f32_e32 v219, v254, v219
	v_cvt_pk_fp8_f32 v250, v179, v254 op_sel:[0,0,1]
	s_waitcnt lgkmcnt(2)
	v_mfma_scale_f32_32x32x64_f8f6f4 v[98:113], v[222:229], v[138:145], v[98:113], v194, v193 op_sel_hi:[0,0,0]
	ds_read_b128 v[222:225], v185 offset:38912
	ds_read_b128 v[226:229], v186 offset:38912
	v_exp_f32_e32 v0, v70
	v_exp_f32_e32 v177, v71
	v_exp_f32_e32 v179, v72
	v_exp_f32_e32 v254, v73
	v_add_f32_e32 v219, v0, v219
	v_add_f32_e32 v219, v177, v219
	v_cvt_pk_fp8_f32 v251, v0, v177
	v_add_f32_e32 v219, v179, v219
	v_add_f32_e32 v219, v254, v219
	v_cvt_pk_fp8_f32 v251, v179, v254 op_sel:[0,0,1]
	v_exp_f32_e32 v0, v74
	v_exp_f32_e32 v177, v75
	v_exp_f32_e32 v179, v76
	v_exp_f32_e32 v254, v77
	v_add_f32_e32 v219, v0, v219
	v_add_f32_e32 v219, v177, v219
	v_cvt_pk_fp8_f32 v252, v0, v177
	v_add_f32_e32 v219, v179, v219
	v_add_f32_e32 v219, v254, v219
	v_cvt_pk_fp8_f32 v252, v179, v254 op_sel:[0,0,1]
	s_waitcnt lgkmcnt(2)
	v_mfma_scale_f32_32x32x64_f8f6f4 v[114:129], v[90:97], v[130:137], v[114:129], v194, v193 op_sel_hi:[0,0,0]
	v_exp_f32_e32 v0, v78
	v_exp_f32_e32 v177, v79
	v_exp_f32_e32 v179, v80
	v_exp_f32_e32 v254, v81
	v_add_f32_e32 v219, v0, v219
	v_add_f32_e32 v219, v177, v219
	v_cvt_pk_fp8_f32 v253, v0, v177
	v_add_f32_e32 v219, v179, v219
	v_add_f32_e32 v219, v254, v219
	v_cvt_pk_fp8_f32 v253, v179, v254 op_sel:[0,0,1]
	ds_read_b128 v[90:93], v185 offset:0
	ds_read_b128 v[94:97], v186 offset:0
	ds_read_b128 v[82:85], v185 offset:2048
	ds_read_b128 v[86:89], v186 offset:2048
	ds_read_b128 v[74:77], v185 offset:4096
	ds_read_b128 v[78:81], v186 offset:4096
	ds_read_b128 v[66:69], v185 offset:6144
	ds_read_b128 v[70:73], v186 offset:6144
	s_waitcnt lgkmcnt(8)
	v_mfma_scale_f32_32x32x64_f8f6f4 v[98:113], v[222:229], v[130:137], v[98:113], v194, v193 op_sel_hi:[0,0,0]
	v_mov_b32_e32 v0, v219
	s_nop 1
	v_permlane32_swap_b32_e32 v219, v0
	v_add_f32_e32 v219, v219, v0
	v_fma_f32 v209, v209, v218, v219
	v_max_f32_e32 v177, v114, v115
	v_max3_f32 v177, v177, v116, v117
	v_max3_f32 v177, v177, v118, v119
	v_max3_f32 v177, v177, v120, v121
	v_max3_f32 v177, v177, v122, v123
	v_max3_f32 v177, v177, v124, v125
	v_max3_f32 v177, v177, v126, v127
	v_max3_f32 v177, v177, v128, v129
	s_waitcnt lgkmcnt(6)
	v_mfma_scale_f32_32x32x64_f8f6f4 v[50:65], v[246:253], v[90:97], v[50:65], v194, v194 op_sel_hi:[0,0,0]
	s_waitcnt lgkmcnt(4)
	v_mfma_scale_f32_32x32x64_f8f6f4 v[34:49], v[246:253], v[82:89], v[34:49], v194, v194 op_sel_hi:[0,0,0]
	s_waitcnt vmcnt(2)
	s_waitcnt lgkmcnt(0)
	s_barrier
	s_waitcnt lgkmcnt(2)
	v_mfma_scale_f32_32x32x64_f8f6f4 v[18:33], v[246:253], v[74:81], v[18:33], v194, v194 op_sel_hi:[0,0,0]
	s_add_i32 m0, s98, 0x0
	s_nop 0
	global_load_lds_dwordx4 v176, s[18:19]
	s_add_i32 m0, s98, 0x4000
	s_nop 0
	global_load_lds_dwordx4 v178, s[16:17]
	v_add_u32_e32 v176, 0x2000, v176
	v_add_u32_e32 v178, 0x20000, v178
	s_waitcnt lgkmcnt(0)
	v_mfma_scale_f32_32x32x64_f8f6f4 v[2:17], v[246:253], v[66:73], v[2:17], v194, v194 op_sel_hi:[0,0,0]
	v_max_f32_e32 v0, v98, v99
	v_max3_f32 v0, v0, v100, v101
	v_max3_f32 v0, v0, v102, v103
	v_max3_f32 v0, v0, v104, v105
	v_max3_f32 v0, v0, v106, v107
	v_max3_f32 v0, v0, v108, v109
	v_max3_f32 v0, v0, v110, v111
	v_max3_f32 v0, v0, v112, v113
	v_max_f32_e32 v177, v177, v0
	v_mov_b32_e32 v0, v177
	v_mov_b32_e32 v221, 1.0
	s_nop 0
	v_permlane32_swap_b32_e32 v177, v0
	v_max_f32_e32 v177, v177, v0
	v_cmp_ge_f32_e32 vcc, s90, v177
	s_cmp_eq_u64 vcc, exec
	s_cbranch_scc0 .Lmla_s0_newmax
; __device__ __forceinline__ void finishSM9(f32x16& p0, f32x16& p1, float alpha, float& l_reg, v8i32& p8) {
; #pragma unroll
;   for (int r = 0; r < 16; ++r) { p0[r] = __builtin_amdgcn_exp2f(p0[r]); p1[r] = __builtin_amdgcn_exp2f(p1[r]); }
;   float ps = 0;
; #pragma unroll
;   for (int r = 0; r < 16; ++r) ps += p0[r];
; #pragma unroll
;   for (int r = 0; r < 16; ++r) ps += p1[r];
;   { auto rr = __builtin_amdgcn_permlane32_swap(__float_as_uint(ps), __float_as_uint(ps), false, false);
;     ps = __uint_as_float(rr[0]) + __uint_as_float(rr[1]); }
;   l_reg = l_reg * alpha + ps;
; #pragma unroll
;   for (int g = 0; g < 4; ++g) {
;     int w = __builtin_amdgcn_cvt_pk_fp8_f32(p0[4 * g], p0[4 * g + 1], 0, false); p8[g] = __builtin_amdgcn_cvt_pk_fp8_f32(p0[4 * g + 2], p0[4 * g + 3], w, true);
;     int u = __builtin_amdgcn_cvt_pk_fp8_f32(p1[4 * g], p1[4 * g + 1], 0, false); p8[4 + g] = __builtin_amdgcn_cvt_pk_fp8_f32(p1[4 * g + 2], p1[4 * g + 3], u, true); }
; }
; __device__ __forceinline__ void pv8(f32x16* o, const char* Vt, const v8i32 p8, int r32, int hi) {
;   const int sw = (r32 >> 2) & 3, a0 = r32 * 64 + (((hi * 2) ^ sw) << 4), a1 = r32 * 64 + (((hi * 2 + 1) ^ sw) << 4);
; #pragma unroll
;   for (int d0 = 0; d0 < 4; ++d0) {
;     const v8i32 vf = cat8(*reinterpret_cast<const v4i32*>(Vt + d0 * 2048 + a0), *reinterpret_cast<const v4i32*>(Vt + d0 * 2048 + a1));
;     o[d0] = __builtin_amdgcn_mfma_scale_f32_32x32x64_f8f6f4(p8, vf, o[d0], 0, 0, 0, 127, 0, 127); }
; }
; __device__ __forceinline__ void qkt9(f32x16& p0, f32x16& p1, const char* Kn, const char* Kr, const v8i32* qf, const float init, int r32, int hi) {
; #pragma unroll
;   for (int r = 0; r < 16; ++r) { p0[r] = init; p1[r] = init; }
; #pragma unroll
;   for (int s = 0; s < 2; ++s) { const int c0 = s * 4 + hi * 2;
;     const v8i32 a0 = cat8(*reinterpret_cast<const v4i32*>(Kn + KN8SW(r32, c0)), *reinterpret_cast<const v4i32*>(Kn + KN8SW(r32, c0 + 1)));
;     const v8i32 a1 = cat8(*reinterpret_cast<const v4i32*>(Kn + 4096 + KN8SW(r32, c0)), *reinterpret_cast<const v4i32*>(Kn + 4096 + KN8SW(r32, c0 + 1)));
;     p0 = __builtin_amdgcn_mfma_scale_f32_32x32x64_f8f6f4(a0, qf[s], p0, 0, 0, 0, 127, 0, 124);
;     p1 = __builtin_amdgcn_mfma_scale_f32_32x32x64_f8f6f4(a1, qf[s], p1, 0, 0, 0, 127, 0, 124); }
;   { const int c0 = hi * 2;
.Lmla_s0_cont:
	ds_read_b128 v[82:85], v166 offset:16384
	ds_read_b128 v[86:89], v167 offset:16384
	ds_read_b128 v[222:225], v166 offset:20480
	ds_read_b128 v[226:229], v167 offset:20480
	v_exp_f32_e32 v0, v114
	v_exp_f32_e32 v177, v115
	v_exp_f32_e32 v179, v116
	v_exp_f32_e32 v254, v117
	v_add_f32_e32 v219, v0, v177
	v_cvt_pk_fp8_f32 v246, v0, v177
	v_add_f32_e32 v219, v179, v219
	v_add_f32_e32 v219, v254, v219
	v_cvt_pk_fp8_f32 v246, v179, v254 op_sel:[0,0,1]
	s_waitcnt lgkmcnt(2)
	v_mfma_scale_f32_32x32x64_f8f6f4 v[82:97], v[82:89], v[146:153], v[230:245], v194, v193 op_sel_hi:[0,0,0]
	v_exp_f32_e32 v0, v118
	v_exp_f32_e32 v177, v119
	v_exp_f32_e32 v179, v120
	v_exp_f32_e32 v254, v121
	v_add_f32_e32 v219, v0, v219
	v_add_f32_e32 v219, v177, v219
	v_cvt_pk_fp8_f32 v247, v0, v177
	v_add_f32_e32 v219, v179, v219
	v_add_f32_e32 v219, v254, v219
	v_cvt_pk_fp8_f32 v247, v179, v254 op_sel:[0,0,1]
	ds_read_b128 v[114:117], v168 offset:16384
	ds_read_b128 v[118:121], v169 offset:16384
	s_waitcnt lgkmcnt(2)
	v_mfma_scale_f32_32x32x64_f8f6f4 v[66:81], v[222:229], v[146:153], v[230:245], v194, v193 op_sel_hi:[0,0,0]
	ds_read_b128 v[222:225], v168 offset:20480
	ds_read_b128 v[226:229], v169 offset:20480
	v_exp_f32_e32 v0, v122
	v_exp_f32_e32 v177, v123
	v_exp_f32_e32 v179, v124
	v_exp_f32_e32 v254, v125
	v_add_f32_e32 v219, v0, v219
	v_add_f32_e32 v219, v177, v219
	v_cvt_pk_fp8_f32 v248, v0, v177
	v_add_f32_e32 v219, v179, v219
	v_add_f32_e32 v219, v254, v219
	v_cvt_pk_fp8_f32 v248, v179, v254 op_sel:[0,0,1]
	v_exp_f32_e32 v0, v126
	v_exp_f32_e32 v177, v127
	v_exp_f32_e32 v179, v128
	v_exp_f32_e32 v254, v129
	v_add_f32_e32 v219, v0, v219
	v_add_f32_e32 v219, v177, v219
	v_cvt_pk_fp8_f32 v249, v0, v177
	v_add_f32_e32 v219, v179, v219
	v_add_f32_e32 v219, v254, v219
	v_cvt_pk_fp8_f32 v249, v179, v254 op_sel:[0,0,1]
	ds_read_b128 v[122:125], v170 offset:32768
	ds_read_b128 v[126:129], v171 offset:32768
	s_waitcnt lgkmcnt(4)
	v_mfma_scale_f32_32x32x64_f8f6f4 v[82:97], v[114:121], v[138:145], v[82:97], v194, v193 op_sel_hi:[0,0,0]
	v_exp_f32_e32 v0, v98
	v_exp_f32_e32 v177, v99
	v_exp_f32_e32 v179, v100
	v_exp_f32_e32 v254, v101
	v_add_f32_e32 v219, v0, v219
	v_add_f32_e32 v219, v177, v219
	v_cvt_pk_fp8_f32 v250, v0, v177
	v_add_f32_e32 v219, v179, v219
	v_add_f32_e32 v219, v254, v219
	v_cvt_pk_fp8_f32 v250, v179, v254 op_sel:[0,0,1]
	s_waitcnt lgkmcnt(2)
	v_mfma_scale_f32_32x32x64_f8f6f4 v[66:81], v[222:229], v[138:145], v[66:81], v194, v193 op_sel_hi:[0,0,0]
	ds_read_b128 v[222:225], v170 offset:34816
	ds_read_b128 v[226:229], v171 offset:34816
	v_exp_f32_e32 v0, v102
	v_exp_f32_e32 v177, v103
	v_exp_f32_e32 v179, v104
	v_exp_f32_e32 v254, v105
	v_add_f32_e32 v219, v0, v219
	v_add_f32_e32 v219, v177, v219
	v_cvt_pk_fp8_f32 v251, v0, v177
	v_add_f32_e32 v219, v179, v219
	v_add_f32_e32 v219, v254, v219
	v_cvt_pk_fp8_f32 v251, v179, v254 op_sel:[0,0,1]
	v_exp_f32_e32 v0, v106
	v_exp_f32_e32 v177, v107
	v_exp_f32_e32 v179, v108
	v_exp_f32_e32 v254, v109
	v_add_f32_e32 v219, v0, v219
	v_add_f32_e32 v219, v177, v219
	v_cvt_pk_fp8_f32 v252, v0, v177
	v_add_f32_e32 v219, v179, v219
	v_add_f32_e32 v219, v254, v219
	v_cvt_pk_fp8_f32 v252, v179, v254 op_sel:[0,0,1]
	s_waitcnt lgkmcnt(2)
	v_mfma_scale_f32_32x32x64_f8f6f4 v[82:97], v[122:129], v[130:137], v[82:97], v194, v193 op_sel_hi:[0,0,0]
	v_exp_f32_e32 v0, v110
	v_exp_f32_e32 v177, v111
	v_exp_f32_e32 v179, v112
	v_exp_f32_e32 v254, v113
	v_add_f32_e32 v219, v0, v219
	v_add_f32_e32 v219, v177, v219
	v_cvt_pk_fp8_f32 v253, v0, v177
	v_add_f32_e32 v219, v179, v219
	v_add_f32_e32 v219, v254, v219
	v_cvt_pk_fp8_f32 v253, v179, v254 op_sel:[0,0,1]
	ds_read_b128 v[122:125], v185 offset:8192
	ds_read_b128 v[126:129], v186 offset:8192
	ds_read_b128 v[114:117], v185 offset:10240
	ds_read_b128 v[118:121], v186 offset:10240
	ds_read_b128 v[106:109], v185 offset:12288
	ds_read_b128 v[110:113], v186 offset:12288
	ds_read_b128 v[98:101], v185 offset:14336
	ds_read_b128 v[102:105], v186 offset:14336
	s_waitcnt lgkmcnt(8)
	v_mfma_scale_f32_32x32x64_f8f6f4 v[66:81], v[222:229], v[130:137], v[66:81], v194, v193 op_sel_hi:[0,0,0]
	v_mov_b32_e32 v0, v219
	s_nop 1
	v_permlane32_swap_b32_e32 v219, v0
	v_add_f32_e32 v219, v219, v0
	v_fma_f32 v209, v209, v221, v219
	v_max_f32_e32 v177, v82, v83
	v_max3_f32 v177, v177, v84, v85
	v_max3_f32 v177, v177, v86, v87
	v_max3_f32 v177, v177, v88, v89
	v_max3_f32 v177, v177, v90, v91
	v_max3_f32 v177, v177, v92, v93
	v_max3_f32 v177, v177, v94, v95
	v_max3_f32 v177, v177, v96, v97
	s_waitcnt lgkmcnt(6)
	v_mfma_scale_f32_32x32x64_f8f6f4 v[50:65], v[246:253], v[122:129], v[50:65], v194, v194 op_sel_hi:[0,0,0]
	s_waitcnt lgkmcnt(4)
	v_mfma_scale_f32_32x32x64_f8f6f4 v[34:49], v[246:253], v[114:121], v[34:49], v194, v194 op_sel_hi:[0,0,0]
	s_waitcnt vmcnt(2)
	s_waitcnt lgkmcnt(0)
	s_barrier
	s_waitcnt lgkmcnt(2)
	v_mfma_scale_f32_32x32x64_f8f6f4 v[18:33], v[246:253], v[106:113], v[18:33], v194, v194 op_sel_hi:[0,0,0]
	s_add_i32 m0, s98, 0x2000
	s_nop 0
	global_load_lds_dwordx4 v176, s[18:19]
	s_add_i32 m0, s98, 0x6000
	s_nop 0
	global_load_lds_dwordx4 v178, s[16:17]
	v_add_u32_e32 v176, 0x2000, v176
	v_add_u32_e32 v178, 0x20000, v178
	s_waitcnt lgkmcnt(0)
	v_mfma_scale_f32_32x32x64_f8f6f4 v[2:17], v[246:253], v[98:105], v[2:17], v194, v194 op_sel_hi:[0,0,0]
	v_max_f32_e32 v0, v66, v67
	v_max3_f32 v0, v0, v68, v69
	v_max3_f32 v0, v0, v70, v71
	v_max3_f32 v0, v0, v72, v73
	v_max3_f32 v0, v0, v74, v75
	v_max3_f32 v0, v0, v76, v77
	v_max3_f32 v0, v0, v78, v79
	v_max3_f32 v0, v0, v80, v81
	v_max_f32_e32 v177, v177, v0
	v_mov_b32_e32 v0, v177
	v_mov_b32_e32 v218, 1.0
	s_nop 0
	v_permlane32_swap_b32_e32 v177, v0
	v_max_f32_e32 v177, v177, v0
	v_cmp_ge_f32_e32 vcc, s90, v177
	s_cmp_eq_u64 vcc, exec
	s_cbranch_scc0 .Lmla_s1_newmax
; __device__ __forceinline__ void finishSM9(f32x16& p0, f32x16& p1, float alpha, float& l_reg, v8i32& p8) {
; #pragma unroll
;   for (int r = 0; r < 16; ++r) { p0[r] = __builtin_amdgcn_exp2f(p0[r]); p1[r] = __builtin_amdgcn_exp2f(p1[r]); }
;   float ps = 0;
; #pragma unroll
;   for (int r = 0; r < 16; ++r) ps += p0[r];
; #pragma unroll
;   for (int r = 0; r < 16; ++r) ps += p1[r];
;   { auto rr = __builtin_amdgcn_permlane32_swap(__float_as_uint(ps), __float_as_uint(ps), false, false);
;     ps = __uint_as_float(rr[0]) + __uint_as_float(rr[1]); }
;   l_reg = l_reg * alpha + ps;
; #pragma unroll
;   for (int g = 0; g < 4; ++g) {
;     int w = __builtin_amdgcn_cvt_pk_fp8_f32(p0[4 * g], p0[4 * g + 1], 0, false); p8[g] = __builtin_amdgcn_cvt_pk_fp8_f32(p0[4 * g + 2], p0[4 * g + 3], w, true);
;     int u = __builtin_amdgcn_cvt_pk_fp8_f32(p1[4 * g], p1[4 * g + 1], 0, false); p8[4 + g] = __builtin_amdgcn_cvt_pk_fp8_f32(p1[4 * g + 2], p1[4 * g + 3], u, true); }
; }
; __device__ __forceinline__ void pv8(f32x16* o, const char* Vt, const v8i32 p8, int r32, int hi) {
;   const int sw = (r32 >> 2) & 3, a0 = r32 * 64 + (((hi * 2) ^ sw) << 4), a1 = r32 * 64 + (((hi * 2 + 1) ^ sw) << 4);
; #pragma unroll
;   for (int d0 = 0; d0 < 4; ++d0) {
;     const v8i32 vf = cat8(*reinterpret_cast<const v4i32*>(Vt + d0 * 2048 + a0), *reinterpret_cast<const v4i32*>(Vt + d0 * 2048 + a1));
;     o[d0] = __builtin_amdgcn_mfma_scale_f32_32x32x64_f8f6f4(p8, vf, o[d0], 0, 0, 0, 127, 0, 127); }
; }
; __device__ __forceinline__ void qkt9(f32x16& p0, f32x16& p1, const char* Kn, const char* Kr, const v8i32* qf, const float init, int r32, int hi) {
; #pragma unroll
;   for (int r = 0; r < 16; ++r) { p0[r] = init; p1[r] = init; }
; #pragma unroll
;   for (int s = 0; s < 2; ++s) { const int c0 = s * 4 + hi * 2;
;     const v8i32 a0 = cat8(*reinterpret_cast<const v4i32*>(Kn + KN8SW(r32, c0)), *reinterpret_cast<const v4i32*>(Kn + KN8SW(r32, c0 + 1)));
;     const v8i32 a1 = cat8(*reinterpret_cast<const v4i32*>(Kn + 4096 + KN8SW(r32, c0)), *reinterpret_cast<const v4i32*>(Kn + 4096 + KN8SW(r32, c0 + 1)));
;     p0 = __builtin_amdgcn_mfma_scale_f32_32x32x64_f8f6f4(a0, qf[s], p0, 0, 0, 0, 127, 0, 124);
;     p1 = __builtin_amdgcn_mfma_scale_f32_32x32x64_f8f6f4(a1, qf[s], p1, 0, 0, 0, 127, 0, 124); }
;   { const int c0 = hi * 2;
.Lmla_s1_cont:
	ds_read_b128 v[114:117], v166 offset:24576
	ds_read_b128 v[118:121], v167 offset:24576
	ds_read_b128 v[222:225], v166 offset:28672
	ds_read_b128 v[226:229], v167 offset:28672
	v_exp_f32_e32 v0, v82
	v_exp_f32_e32 v177, v83
	v_exp_f32_e32 v179, v84
	v_exp_f32_e32 v254, v85
	v_add_f32_e32 v219, v0, v177
	v_cvt_pk_fp8_f32 v246, v0, v177
	v_add_f32_e32 v219, v179, v219
	v_add_f32_e32 v219, v254, v219
	v_cvt_pk_fp8_f32 v246, v179, v254 op_sel:[0,0,1]
	s_waitcnt lgkmcnt(2)
	v_mfma_scale_f32_32x32x64_f8f6f4 v[114:129], v[114:121], v[146:153], v[230:245], v194, v193 op_sel_hi:[0,0,0]
	v_exp_f32_e32 v0, v86
	v_exp_f32_e32 v177, v87
	v_exp_f32_e32 v179, v88
	v_exp_f32_e32 v254, v89
	v_add_f32_e32 v219, v0, v219
	v_add_f32_e32 v219, v177, v219
	v_cvt_pk_fp8_f32 v247, v0, v177
	v_add_f32_e32 v219, v179, v219
	v_add_f32_e32 v219, v254, v219
	v_cvt_pk_fp8_f32 v247, v179, v254 op_sel:[0,0,1]
	ds_read_b128 v[82:85], v168 offset:24576
	ds_read_b128 v[86:89], v169 offset:24576
	s_waitcnt lgkmcnt(2)
	v_mfma_scale_f32_32x32x64_f8f6f4 v[98:113], v[222:229], v[146:153], v[230:245], v194, v193 op_sel_hi:[0,0,0]
	ds_read_b128 v[222:225], v168 offset:28672
	ds_read_b128 v[226:229], v169 offset:28672
	v_exp_f32_e32 v0, v90
	v_exp_f32_e32 v177, v91
	v_exp_f32_e32 v179, v92
	v_exp_f32_e32 v254, v93
	v_add_f32_e32 v219, v0, v219
	v_add_f32_e32 v219, v177, v219
	v_cvt_pk_fp8_f32 v248, v0, v177
	v_add_f32_e32 v219, v179, v219
	v_add_f32_e32 v219, v254, v219
	v_cvt_pk_fp8_f32 v248, v179, v254 op_sel:[0,0,1]
	v_exp_f32_e32 v0, v94
	v_exp_f32_e32 v177, v95
	v_exp_f32_e32 v179, v96
	v_exp_f32_e32 v254, v97
	v_add_f32_e32 v219, v0, v219
	v_add_f32_e32 v219, v177, v219
	v_cvt_pk_fp8_f32 v249, v0, v177
	v_add_f32_e32 v219, v179, v219
	v_add_f32_e32 v219, v254, v219
	v_cvt_pk_fp8_f32 v249, v179, v254 op_sel:[0,0,1]
	ds_read_b128 v[90:93], v170 offset:36864
	ds_read_b128 v[94:97], v171 offset:36864
	s_waitcnt lgkmcnt(4)
	v_mfma_scale_f32_32x32x64_f8f6f4 v[114:129], v[82:89], v[138:145], v[114:129], v194, v193 op_sel_hi:[0,0,0]
	v_exp_f32_e32 v0, v66
	v_exp_f32_e32 v177, v67
	v_exp_f32_e32 v179, v68
	v_exp_f32_e32 v254, v69
	v_add_f32_e32 v219, v0, v219
	v_add_f32_e32 v219, v177, v219
	v_cvt_pk_fp8_f32 v250, v0, v177
	v_add_f32_e32 v219, v179, v219
	v_add_f32_e32 v219, v254, v219
	v_cvt_pk_fp8_f32 v250, v179, v254 op_sel:[0,0,1]
	s_waitcnt lgkmcnt(2)
	v_mfma_scale_f32_32x32x64_f8f6f4 v[98:113], v[222:229], v[138:145], v[98:113], v194, v193 op_sel_hi:[0,0,0]
	ds_read_b128 v[222:225], v170 offset:38912
	ds_read_b128 v[226:229], v171 offset:38912
	v_exp_f32_e32 v0, v70
	v_exp_f32_e32 v177, v71
	v_exp_f32_e32 v179, v72
	v_exp_f32_e32 v254, v73
	v_add_f32_e32 v219, v0, v219
	v_add_f32_e32 v219, v177, v219
	v_cvt_pk_fp8_f32 v251, v0, v177
	v_add_f32_e32 v219, v179, v219
	v_add_f32_e32 v219, v254, v219
	v_cvt_pk_fp8_f32 v251, v179, v254 op_sel:[0,0,1]
	v_exp_f32_e32 v0, v74
	v_exp_f32_e32 v177, v75
	v_exp_f32_e32 v179, v76
	v_exp_f32_e32 v254, v77
	v_add_f32_e32 v219, v0, v219
	v_add_f32_e32 v219, v177, v219
	v_cvt_pk_fp8_f32 v252, v0, v177
	v_add_f32_e32 v219, v179, v219
	v_add_f32_e32 v219, v254, v219
	v_cvt_pk_fp8_f32 v252, v179, v254 op_sel:[0,0,1]
	s_waitcnt lgkmcnt(2)
	v_mfma_scale_f32_32x32x64_f8f6f4 v[114:129], v[90:97], v[130:137], v[114:129], v194, v193 op_sel_hi:[0,0,0]
	v_exp_f32_e32 v0, v78
	v_exp_f32_e32 v177, v79
	v_exp_f32_e32 v179, v80
	v_exp_f32_e32 v254, v81
	v_add_f32_e32 v219, v0, v219
	v_add_f32_e32 v219, v177, v219
	v_cvt_pk_fp8_f32 v253, v0, v177
	v_add_f32_e32 v219, v179, v219
	v_add_f32_e32 v219, v254, v219
	v_cvt_pk_fp8_f32 v253, v179, v254 op_sel:[0,0,1]
	ds_read_b128 v[90:93], v170 offset:0
	ds_read_b128 v[94:97], v171 offset:0
	ds_read_b128 v[82:85], v170 offset:2048
	ds_read_b128 v[86:89], v171 offset:2048
	ds_read_b128 v[74:77], v170 offset:4096
	ds_read_b128 v[78:81], v171 offset:4096
	ds_read_b128 v[66:69], v170 offset:6144
	ds_read_b128 v[70:73], v171 offset:6144
	s_waitcnt lgkmcnt(8)
	v_mfma_scale_f32_32x32x64_f8f6f4 v[98:113], v[222:229], v[130:137], v[98:113], v194, v193 op_sel_hi:[0,0,0]
	v_mov_b32_e32 v0, v219
	s_nop 1
	v_permlane32_swap_b32_e32 v219, v0
	v_add_f32_e32 v219, v219, v0
	v_fma_f32 v209, v209, v218, v219
	v_max_f32_e32 v177, v114, v115
	v_max3_f32 v177, v177, v116, v117
	v_max3_f32 v177, v177, v118, v119
	v_max3_f32 v177, v177, v120, v121
	v_max3_f32 v177, v177, v122, v123
	v_max3_f32 v177, v177, v124, v125
	v_max3_f32 v177, v177, v126, v127
	v_max3_f32 v177, v177, v128, v129
	s_waitcnt lgkmcnt(6)
	v_mfma_scale_f32_32x32x64_f8f6f4 v[50:65], v[246:253], v[90:97], v[50:65], v194, v194 op_sel_hi:[0,0,0]
	s_waitcnt lgkmcnt(4)
	v_mfma_scale_f32_32x32x64_f8f6f4 v[34:49], v[246:253], v[82:89], v[34:49], v194, v194 op_sel_hi:[0,0,0]
	s_waitcnt vmcnt(2)
	s_waitcnt lgkmcnt(0)
	s_barrier
	s_waitcnt lgkmcnt(2)
	v_mfma_scale_f32_32x32x64_f8f6f4 v[18:33], v[246:253], v[74:81], v[18:33], v194, v194 op_sel_hi:[0,0,0]
	s_add_i32 m0, s98, 0xa800
	s_nop 0
	global_load_lds_dwordx4 v176, s[18:19]
	s_add_i32 m0, s98, 0xe800
	s_nop 0
	global_load_lds_dwordx4 v178, s[16:17]
	v_add_u32_e32 v176, 0x2000, v176
	v_add_u32_e32 v178, 0x20000, v178
	s_waitcnt lgkmcnt(0)
	v_mfma_scale_f32_32x32x64_f8f6f4 v[2:17], v[246:253], v[66:73], v[2:17], v194, v194 op_sel_hi:[0,0,0]
	v_max_f32_e32 v0, v98, v99
	v_max3_f32 v0, v0, v100, v101
	v_max3_f32 v0, v0, v102, v103
	v_max3_f32 v0, v0, v104, v105
	v_max3_f32 v0, v0, v106, v107
	v_max3_f32 v0, v0, v108, v109
	v_max3_f32 v0, v0, v110, v111
	v_max3_f32 v0, v0, v112, v113
	v_max_f32_e32 v177, v177, v0
	v_mov_b32_e32 v0, v177
	v_mov_b32_e32 v221, 1.0
	s_nop 0
	v_permlane32_swap_b32_e32 v177, v0
	v_max_f32_e32 v177, v177, v0
	v_cmp_ge_f32_e32 vcc, s90, v177
	s_cmp_eq_u64 vcc, exec
	s_cbranch_scc0 .Lmla_s2_newmax
; __device__ __forceinline__ void finishSM9(f32x16& p0, f32x16& p1, float alpha, float& l_reg, v8i32& p8) {
; #pragma unroll
;   for (int r = 0; r < 16; ++r) { p0[r] = __builtin_amdgcn_exp2f(p0[r]); p1[r] = __builtin_amdgcn_exp2f(p1[r]); }
;   float ps = 0;
; #pragma unroll
;   for (int r = 0; r < 16; ++r) ps += p0[r];
; #pragma unroll
;   for (int r = 0; r < 16; ++r) ps += p1[r];
;   { auto rr = __builtin_amdgcn_permlane32_swap(__float_as_uint(ps), __float_as_uint(ps), false, false);
;     ps = __uint_as_float(rr[0]) + __uint_as_float(rr[1]); }
;   l_reg = l_reg * alpha + ps;
; #pragma unroll
;   for (int g = 0; g < 4; ++g) {
;     int w = __builtin_amdgcn_cvt_pk_fp8_f32(p0[4 * g], p0[4 * g + 1], 0, false); p8[g] = __builtin_amdgcn_cvt_pk_fp8_f32(p0[4 * g + 2], p0[4 * g + 3], w, true);
;     int u = __builtin_amdgcn_cvt_pk_fp8_f32(p1[4 * g], p1[4 * g + 1], 0, false); p8[4 + g] = __builtin_amdgcn_cvt_pk_fp8_f32(p1[4 * g + 2], p1[4 * g + 3], u, true); }
; }
; __device__ __forceinline__ void pv8(f32x16* o, const char* Vt, const v8i32 p8, int r32, int hi) {
;   const int sw = (r32 >> 2) & 3, a0 = r32 * 64 + (((hi * 2) ^ sw) << 4), a1 = r32 * 64 + (((hi * 2 + 1) ^ sw) << 4);
; #pragma unroll
;   for (int d0 = 0; d0 < 4; ++d0) {
;     const v8i32 vf = cat8(*reinterpret_cast<const v4i32*>(Vt + d0 * 2048 + a0), *reinterpret_cast<const v4i32*>(Vt + d0 * 2048 + a1));
;     o[d0] = __builtin_amdgcn_mfma_scale_f32_32x32x64_f8f6f4(p8, vf, o[d0], 0, 0, 0, 127, 0, 127); }
; }
; __device__ __forceinline__ void qkt9(f32x16& p0, f32x16& p1, const char* Kn, const char* Kr, const v8i32* qf, const float init, int r32, int hi) {
; #pragma unroll
;   for (int r = 0; r < 16; ++r) { p0[r] = init; p1[r] = init; }
; #pragma unroll
;   for (int s = 0; s < 2; ++s) { const int c0 = s * 4 + hi * 2;
;     const v8i32 a0 = cat8(*reinterpret_cast<const v4i32*>(Kn + KN8SW(r32, c0)), *reinterpret_cast<const v4i32*>(Kn + KN8SW(r32, c0 + 1)));
;     const v8i32 a1 = cat8(*reinterpret_cast<const v4i32*>(Kn + 4096 + KN8SW(r32, c0)), *reinterpret_cast<const v4i32*>(Kn + 4096 + KN8SW(r32, c0 + 1)));
;     p0 = __builtin_amdgcn_mfma_scale_f32_32x32x64_f8f6f4(a0, qf[s], p0, 0, 0, 0, 127, 0, 124);
;     p1 = __builtin_amdgcn_mfma_scale_f32_32x32x64_f8f6f4(a1, qf[s], p1, 0, 0, 0, 127, 0, 124); }
;   { const int c0 = hi * 2;
.Lmla_s2_cont:
	ds_read_b128 v[82:85], v215 offset:16384
	ds_read_b128 v[86:89], v216 offset:16384
	ds_read_b128 v[222:225], v215 offset:20480
	ds_read_b128 v[226:229], v216 offset:20480
	v_exp_f32_e32 v0, v114
	v_exp_f32_e32 v177, v115
	v_exp_f32_e32 v179, v116
	v_exp_f32_e32 v254, v117
	v_add_f32_e32 v219, v0, v177
	v_cvt_pk_fp8_f32 v246, v0, v177
	v_add_f32_e32 v219, v179, v219
	v_add_f32_e32 v219, v254, v219
	v_cvt_pk_fp8_f32 v246, v179, v254 op_sel:[0,0,1]
	s_waitcnt lgkmcnt(2)
	v_mfma_scale_f32_32x32x64_f8f6f4 v[82:97], v[82:89], v[146:153], v[230:245], v194, v193 op_sel_hi:[0,0,0]
	v_exp_f32_e32 v0, v118
	v_exp_f32_e32 v177, v119
	v_exp_f32_e32 v179, v120
	v_exp_f32_e32 v254, v121
	v_add_f32_e32 v219, v0, v219
	v_add_f32_e32 v219, v177, v219
	v_cvt_pk_fp8_f32 v247, v0, v177
	v_add_f32_e32 v219, v179, v219
	v_add_f32_e32 v219, v254, v219
	v_cvt_pk_fp8_f32 v247, v179, v254 op_sel:[0,0,1]
	ds_read_b128 v[114:117], v213 offset:16384
	ds_read_b128 v[118:121], v214 offset:16384
	s_waitcnt lgkmcnt(2)
	v_mfma_scale_f32_32x32x64_f8f6f4 v[66:81], v[222:229], v[146:153], v[230:245], v194, v193 op_sel_hi:[0,0,0]
	ds_read_b128 v[222:225], v213 offset:20480
	ds_read_b128 v[226:229], v214 offset:20480
	v_exp_f32_e32 v0, v122
	v_exp_f32_e32 v177, v123
	v_exp_f32_e32 v179, v124
	v_exp_f32_e32 v254, v125
	v_add_f32_e32 v219, v0, v219
	v_add_f32_e32 v219, v177, v219
	v_cvt_pk_fp8_f32 v248, v0, v177
	v_add_f32_e32 v219, v179, v219
	v_add_f32_e32 v219, v254, v219
	v_cvt_pk_fp8_f32 v248, v179, v254 op_sel:[0,0,1]
	v_exp_f32_e32 v0, v126
	v_exp_f32_e32 v177, v127
	v_exp_f32_e32 v179, v128
	v_exp_f32_e32 v254, v129
	v_add_f32_e32 v219, v0, v219
	v_add_f32_e32 v219, v177, v219
	v_cvt_pk_fp8_f32 v249, v0, v177
	v_add_f32_e32 v219, v179, v219
	v_add_f32_e32 v219, v254, v219
	v_cvt_pk_fp8_f32 v249, v179, v254 op_sel:[0,0,1]
	ds_read_b128 v[122:125], v185 offset:32768
	ds_read_b128 v[126:129], v186 offset:32768
	s_waitcnt lgkmcnt(4)
	v_mfma_scale_f32_32x32x64_f8f6f4 v[82:97], v[114:121], v[138:145], v[82:97], v194, v193 op_sel_hi:[0,0,0]
	v_exp_f32_e32 v0, v98
	v_exp_f32_e32 v177, v99
	v_exp_f32_e32 v179, v100
	v_exp_f32_e32 v254, v101
	v_add_f32_e32 v219, v0, v219
	v_add_f32_e32 v219, v177, v219
	v_cvt_pk_fp8_f32 v250, v0, v177
	v_add_f32_e32 v219, v179, v219
	v_add_f32_e32 v219, v254, v219
	v_cvt_pk_fp8_f32 v250, v179, v254 op_sel:[0,0,1]
	s_waitcnt lgkmcnt(2)
	v_mfma_scale_f32_32x32x64_f8f6f4 v[66:81], v[222:229], v[138:145], v[66:81], v194, v193 op_sel_hi:[0,0,0]
	ds_read_b128 v[222:225], v185 offset:34816
	ds_read_b128 v[226:229], v186 offset:34816
	v_exp_f32_e32 v0, v102
	v_exp_f32_e32 v177, v103
	v_exp_f32_e32 v179, v104
	v_exp_f32_e32 v254, v105
	v_add_f32_e32 v219, v0, v219
	v_add_f32_e32 v219, v177, v219
	v_cvt_pk_fp8_f32 v251, v0, v177
	v_add_f32_e32 v219, v179, v219
	v_add_f32_e32 v219, v254, v219
	v_cvt_pk_fp8_f32 v251, v179, v254 op_sel:[0,0,1]
	v_exp_f32_e32 v0, v106
	v_exp_f32_e32 v177, v107
	v_exp_f32_e32 v179, v108
	v_exp_f32_e32 v254, v109
	v_add_f32_e32 v219, v0, v219
	v_add_f32_e32 v219, v177, v219
	v_cvt_pk_fp8_f32 v252, v0, v177
	v_add_f32_e32 v219, v179, v219
	v_add_f32_e32 v219, v254, v219
	v_cvt_pk_fp8_f32 v252, v179, v254 op_sel:[0,0,1]
	s_waitcnt lgkmcnt(2)
	v_mfma_scale_f32_32x32x64_f8f6f4 v[82:97], v[122:129], v[130:137], v[82:97], v194, v193 op_sel_hi:[0,0,0]
	v_exp_f32_e32 v0, v110
	v_exp_f32_e32 v177, v111
	v_exp_f32_e32 v179, v112
	v_exp_f32_e32 v254, v113
	v_add_f32_e32 v219, v0, v219
	v_add_f32_e32 v219, v177, v219
	v_cvt_pk_fp8_f32 v253, v0, v177
	v_add_f32_e32 v219, v179, v219
	v_add_f32_e32 v219, v254, v219
	v_cvt_pk_fp8_f32 v253, v179, v254 op_sel:[0,0,1]
	ds_read_b128 v[122:125], v170 offset:8192
	ds_read_b128 v[126:129], v171 offset:8192
	ds_read_b128 v[114:117], v170 offset:10240
	ds_read_b128 v[118:121], v171 offset:10240
	ds_read_b128 v[106:109], v170 offset:12288
	ds_read_b128 v[110:113], v171 offset:12288
	ds_read_b128 v[98:101], v170 offset:14336
	ds_read_b128 v[102:105], v171 offset:14336
	s_waitcnt lgkmcnt(8)
	v_mfma_scale_f32_32x32x64_f8f6f4 v[66:81], v[222:229], v[130:137], v[66:81], v194, v193 op_sel_hi:[0,0,0]
	v_mov_b32_e32 v0, v219
	s_nop 1
	v_permlane32_swap_b32_e32 v219, v0
	v_add_f32_e32 v219, v219, v0
	v_fma_f32 v209, v209, v221, v219
	v_max_f32_e32 v177, v82, v83
	v_max3_f32 v177, v177, v84, v85
	v_max3_f32 v177, v177, v86, v87
	v_max3_f32 v177, v177, v88, v89
	v_max3_f32 v177, v177, v90, v91
	v_max3_f32 v177, v177, v92, v93
	v_max3_f32 v177, v177, v94, v95
	v_max3_f32 v177, v177, v96, v97
	s_waitcnt lgkmcnt(6)
	v_mfma_scale_f32_32x32x64_f8f6f4 v[50:65], v[246:253], v[122:129], v[50:65], v194, v194 op_sel_hi:[0,0,0]
	s_waitcnt lgkmcnt(4)
	v_mfma_scale_f32_32x32x64_f8f6f4 v[34:49], v[246:253], v[114:121], v[34:49], v194, v194 op_sel_hi:[0,0,0]
	s_waitcnt vmcnt(2)
	s_waitcnt lgkmcnt(0)
	s_barrier
	s_waitcnt lgkmcnt(2)
	v_mfma_scale_f32_32x32x64_f8f6f4 v[18:33], v[246:253], v[106:113], v[18:33], v194, v194 op_sel_hi:[0,0,0]
	s_add_i32 m0, s98, 0xc800
	s_nop 0
	global_load_lds_dwordx4 v176, s[18:19]
	s_add_i32 m0, s98, 0x10800
	s_nop 0
	global_load_lds_dwordx4 v178, s[16:17]
	v_add_u32_e32 v176, 0x2000, v176
	v_add_u32_e32 v178, 0x20000, v178
	s_waitcnt lgkmcnt(0)
	v_mfma_scale_f32_32x32x64_f8f6f4 v[2:17], v[246:253], v[98:105], v[2:17], v194, v194 op_sel_hi:[0,0,0]
	v_max_f32_e32 v0, v66, v67
	v_max3_f32 v0, v0, v68, v69
	v_max3_f32 v0, v0, v70, v71
	v_max3_f32 v0, v0, v72, v73
	v_max3_f32 v0, v0, v74, v75
	v_max3_f32 v0, v0, v76, v77
	v_max3_f32 v0, v0, v78, v79
	v_max3_f32 v0, v0, v80, v81
	v_max_f32_e32 v177, v177, v0
	v_mov_b32_e32 v0, v177
	v_mov_b32_e32 v218, 1.0
	s_nop 0
	v_permlane32_swap_b32_e32 v177, v0
	v_max_f32_e32 v177, v177, v0
	v_cmp_ge_f32_e32 vcc, s90, v177
	s_cmp_eq_u64 vcc, exec
	s_cbranch_scc0 .Lmla_s3_newmax
; __device__ __forceinline__ void finishSM9(f32x16& p0, f32x16& p1, float alpha, float& l_reg, v8i32& p8) {
; #pragma unroll
;   for (int r = 0; r < 16; ++r) { p0[r] = __builtin_amdgcn_exp2f(p0[r]); p1[r] = __builtin_amdgcn_exp2f(p1[r]); }
;   float ps = 0;
; #pragma unroll
;   for (int r = 0; r < 16; ++r) ps += p0[r];
; #pragma unroll
;   for (int r = 0; r < 16; ++r) ps += p1[r];
;   { auto rr = __builtin_amdgcn_permlane32_swap(__float_as_uint(ps), __float_as_uint(ps), false, false);
;     ps = __uint_as_float(rr[0]) + __uint_as_float(rr[1]); }
;   l_reg = l_reg * alpha + ps;
; #pragma unroll
;   for (int g = 0; g < 4; ++g) {
;     int w = __builtin_amdgcn_cvt_pk_fp8_f32(p0[4 * g], p0[4 * g + 1], 0, false); p8[g] = __builtin_amdgcn_cvt_pk_fp8_f32(p0[4 * g + 2], p0[4 * g + 3], w, true);
;     int u = __builtin_amdgcn_cvt_pk_fp8_f32(p1[4 * g], p1[4 * g + 1], 0, false); p8[4 + g] = __builtin_amdgcn_cvt_pk_fp8_f32(p1[4 * g + 2], p1[4 * g + 3], u, true); }
; }
; __device__ __forceinline__ void pv8(f32x16* o, const char* Vt, const v8i32 p8, int r32, int hi) {
;   const int sw = (r32 >> 2) & 3, a0 = r32 * 64 + (((hi * 2) ^ sw) << 4), a1 = r32 * 64 + (((hi * 2 + 1) ^ sw) << 4);
; #pragma unroll
;   for (int d0 = 0; d0 < 4; ++d0) {
;     const v8i32 vf = cat8(*reinterpret_cast<const v4i32*>(Vt + d0 * 2048 + a0), *reinterpret_cast<const v4i32*>(Vt + d0 * 2048 + a1));
;     o[d0] = __builtin_amdgcn_mfma_scale_f32_32x32x64_f8f6f4(p8, vf, o[d0], 0, 0, 0, 127, 0, 127); }
; }
; __device__ __forceinline__ void qkt9(f32x16& p0, f32x16& p1, const char* Kn, const char* Kr, const v8i32* qf, const float init, int r32, int hi) {
; #pragma unroll
;   for (int r = 0; r < 16; ++r) { p0[r] = init; p1[r] = init; }
; #pragma unroll
;   for (int s = 0; s < 2; ++s) { const int c0 = s * 4 + hi * 2;
;     const v8i32 a0 = cat8(*reinterpret_cast<const v4i32*>(Kn + KN8SW(r32, c0)), *reinterpret_cast<const v4i32*>(Kn + KN8SW(r32, c0 + 1)));
;     const v8i32 a1 = cat8(*reinterpret_cast<const v4i32*>(Kn + 4096 + KN8SW(r32, c0)), *reinterpret_cast<const v4i32*>(Kn + 4096 + KN8SW(r32, c0 + 1)));
;     p0 = __builtin_amdgcn_mfma_scale_f32_32x32x64_f8f6f4(a0, qf[s], p0, 0, 0, 0, 127, 0, 124);
;     p1 = __builtin_amdgcn_mfma_scale_f32_32x32x64_f8f6f4(a1, qf[s], p1, 0, 0, 0, 127, 0, 124); }
;   { const int c0 = hi * 2;
.Lmla_s3_cont:
	s_add_i32 s30, s30, 1
	s_cmpk_lt_u32 s30, 63
	s_cbranch_scc1 .Lmla_stag_loop
	ds_read_b128 v[114:117], v215 offset:24576
	ds_read_b128 v[118:121], v216 offset:24576
	ds_read_b128 v[222:225], v215 offset:28672
	ds_read_b128 v[226:229], v216 offset:28672
	v_exp_f32_e32 v0, v82
	v_exp_f32_e32 v177, v83
	v_exp_f32_e32 v179, v84
	v_exp_f32_e32 v254, v85
	v_add_f32_e32 v219, v0, v177
	v_cvt_pk_fp8_f32 v246, v0, v177
	v_add_f32_e32 v219, v179, v219
	v_add_f32_e32 v219, v254, v219
	v_cvt_pk_fp8_f32 v246, v179, v254 op_sel:[0,0,1]
	s_waitcnt lgkmcnt(2)
	v_mfma_scale_f32_32x32x64_f8f6f4 v[114:129], v[114:121], v[146:153], v[230:245], v194, v193 op_sel_hi:[0,0,0]
	v_exp_f32_e32 v0, v86
	v_exp_f32_e32 v177, v87
	v_exp_f32_e32 v179, v88
	v_exp_f32_e32 v254, v89
	v_add_f32_e32 v219, v0, v219
	v_add_f32_e32 v219, v177, v219
	v_cvt_pk_fp8_f32 v247, v0, v177
	v_add_f32_e32 v219, v179, v219
	v_add_f32_e32 v219, v254, v219
	v_cvt_pk_fp8_f32 v247, v179, v254 op_sel:[0,0,1]
	ds_read_b128 v[82:85], v213 offset:24576
	ds_read_b128 v[86:89], v214 offset:24576
	s_waitcnt lgkmcnt(2)
	v_mfma_scale_f32_32x32x64_f8f6f4 v[98:113], v[222:229], v[146:153], v[230:245], v194, v193 op_sel_hi:[0,0,0]
	ds_read_b128 v[222:225], v213 offset:28672
	ds_read_b128 v[226:229], v214 offset:28672
	v_exp_f32_e32 v0, v90
	v_exp_f32_e32 v177, v91
	v_exp_f32_e32 v179, v92
	v_exp_f32_e32 v254, v93
	v_add_f32_e32 v219, v0, v219
	v_add_f32_e32 v219, v177, v219
	v_cvt_pk_fp8_f32 v248, v0, v177
	v_add_f32_e32 v219, v179, v219
	v_add_f32_e32 v219, v254, v219
	v_cvt_pk_fp8_f32 v248, v179, v254 op_sel:[0,0,1]
	v_exp_f32_e32 v0, v94
	v_exp_f32_e32 v177, v95
	v_exp_f32_e32 v179, v96
	v_exp_f32_e32 v254, v97
	v_add_f32_e32 v219, v0, v219
	v_add_f32_e32 v219, v177, v219
	v_cvt_pk_fp8_f32 v249, v0, v177
	v_add_f32_e32 v219, v179, v219
	v_add_f32_e32 v219, v254, v219
	v_cvt_pk_fp8_f32 v249, v179, v254 op_sel:[0,0,1]
	ds_read_b128 v[90:93], v185 offset:36864
	ds_read_b128 v[94:97], v186 offset:36864
	s_waitcnt lgkmcnt(4)
	v_mfma_scale_f32_32x32x64_f8f6f4 v[114:129], v[82:89], v[138:145], v[114:129], v194, v193 op_sel_hi:[0,0,0]
	v_exp_f32_e32 v0, v66
	v_exp_f32_e32 v177, v67
	v_exp_f32_e32 v179, v68
	v_exp_f32_e32 v254, v69
	v_add_f32_e32 v219, v0, v219
	v_add_f32_e32 v219, v177, v219
	v_cvt_pk_fp8_f32 v250, v0, v177
	v_add_f32_e32 v219, v179, v219
	v_add_f32_e32 v219, v254, v219
	v_cvt_pk_fp8_f32 v250, v179, v254 op_sel:[0,0,1]
	s_waitcnt lgkmcnt(2)
	v_mfma_scale_f32_32x32x64_f8f6f4 v[98:113], v[222:229], v[138:145], v[98:113], v194, v193 op_sel_hi:[0,0,0]
	ds_read_b128 v[222:225], v185 offset:38912
	ds_read_b128 v[226:229], v186 offset:38912
	v_exp_f32_e32 v0, v70
	v_exp_f32_e32 v177, v71
	v_exp_f32_e32 v179, v72
	v_exp_f32_e32 v254, v73
	v_add_f32_e32 v219, v0, v219
	v_add_f32_e32 v219, v177, v219
	v_cvt_pk_fp8_f32 v251, v0, v177
	v_add_f32_e32 v219, v179, v219
	v_add_f32_e32 v219, v254, v219
	v_cvt_pk_fp8_f32 v251, v179, v254 op_sel:[0,0,1]
	v_exp_f32_e32 v0, v74
	v_exp_f32_e32 v177, v75
	v_exp_f32_e32 v179, v76
	v_exp_f32_e32 v254, v77
	v_add_f32_e32 v219, v0, v219
	v_add_f32_e32 v219, v177, v219
	v_cvt_pk_fp8_f32 v252, v0, v177
	v_add_f32_e32 v219, v179, v219
	v_add_f32_e32 v219, v254, v219
	v_cvt_pk_fp8_f32 v252, v179, v254 op_sel:[0,0,1]
	s_waitcnt lgkmcnt(2)
	v_mfma_scale_f32_32x32x64_f8f6f4 v[114:129], v[90:97], v[130:137], v[114:129], v194, v193 op_sel_hi:[0,0,0]
	v_exp_f32_e32 v0, v78
	v_exp_f32_e32 v177, v79
	v_exp_f32_e32 v179, v80
	v_exp_f32_e32 v254, v81
	v_add_f32_e32 v219, v0, v219
	v_add_f32_e32 v219, v177, v219
	v_cvt_pk_fp8_f32 v253, v0, v177
	v_add_f32_e32 v219, v179, v219
	v_add_f32_e32 v219, v254, v219
	v_cvt_pk_fp8_f32 v253, v179, v254 op_sel:[0,0,1]
	ds_read_b128 v[90:93], v185 offset:0
	ds_read_b128 v[94:97], v186 offset:0
	ds_read_b128 v[82:85], v185 offset:2048
	ds_read_b128 v[86:89], v186 offset:2048
	ds_read_b128 v[74:77], v185 offset:4096
	ds_read_b128 v[78:81], v186 offset:4096
	ds_read_b128 v[66:69], v185 offset:6144
	ds_read_b128 v[70:73], v186 offset:6144
	s_waitcnt lgkmcnt(8)
	v_mfma_scale_f32_32x32x64_f8f6f4 v[98:113], v[222:229], v[130:137], v[98:113], v194, v193 op_sel_hi:[0,0,0]
	v_mov_b32_e32 v0, v219
	s_nop 1
	v_permlane32_swap_b32_e32 v219, v0
	v_add_f32_e32 v219, v219, v0
	v_fma_f32 v209, v209, v218, v219
	v_max_f32_e32 v177, v114, v115
	v_max3_f32 v177, v177, v116, v117
	v_max3_f32 v177, v177, v118, v119
	v_max3_f32 v177, v177, v120, v121
	v_max3_f32 v177, v177, v122, v123
	v_max3_f32 v177, v177, v124, v125
	v_max3_f32 v177, v177, v126, v127
	v_max3_f32 v177, v177, v128, v129
	s_waitcnt lgkmcnt(6)
	v_mfma_scale_f32_32x32x64_f8f6f4 v[50:65], v[246:253], v[90:97], v[50:65], v194, v194 op_sel_hi:[0,0,0]
	s_waitcnt lgkmcnt(4)
	v_mfma_scale_f32_32x32x64_f8f6f4 v[34:49], v[246:253], v[82:89], v[34:49], v194, v194 op_sel_hi:[0,0,0]
	s_waitcnt vmcnt(2)
	s_waitcnt lgkmcnt(0)
	s_barrier
	s_waitcnt lgkmcnt(2)
	v_mfma_scale_f32_32x32x64_f8f6f4 v[18:33], v[246:253], v[74:81], v[18:33], v194, v194 op_sel_hi:[0,0,0]
	s_waitcnt lgkmcnt(0)
	v_mfma_scale_f32_32x32x64_f8f6f4 v[2:17], v[246:253], v[66:73], v[2:17], v194, v194 op_sel_hi:[0,0,0]
	v_max_f32_e32 v0, v98, v99
	v_max3_f32 v0, v0, v100, v101
	v_max3_f32 v0, v0, v102, v103
	v_max3_f32 v0, v0, v104, v105
	v_max3_f32 v0, v0, v106, v107
	v_max3_f32 v0, v0, v108, v109
	v_max3_f32 v0, v0, v110, v111
	v_max3_f32 v0, v0, v112, v113
	v_max_f32_e32 v177, v177, v0
	v_mov_b32_e32 v0, v177
	v_mov_b32_e32 v221, 1.0
	s_nop 0
	v_permlane32_swap_b32_e32 v177, v0
	v_max_f32_e32 v177, v177, v0
	v_cmp_ge_f32_e32 vcc, s90, v177
	s_cmp_eq_u64 vcc, exec
	s_cbranch_scc0 .Lmla_q0_newmax
; __device__ __forceinline__ void finishSM9(f32x16& p0, f32x16& p1, float alpha, float& l_reg, v8i32& p8) {
; #pragma unroll
;   for (int r = 0; r < 16; ++r) { p0[r] = __builtin_amdgcn_exp2f(p0[r]); p1[r] = __builtin_amdgcn_exp2f(p1[r]); }
;   float ps = 0;
; #pragma unroll
;   for (int r = 0; r < 16; ++r) ps += p0[r];
; #pragma unroll
;   for (int r = 0; r < 16; ++r) ps += p1[r];
;   { auto rr = __builtin_amdgcn_permlane32_swap(__float_as_uint(ps), __float_as_uint(ps), false, false);
;     ps = __uint_as_float(rr[0]) + __uint_as_float(rr[1]); }
;   l_reg = l_reg * alpha + ps;
; #pragma unroll
;   for (int g = 0; g < 4; ++g) {
;     int w = __builtin_amdgcn_cvt_pk_fp8_f32(p0[4 * g], p0[4 * g + 1], 0, false); p8[g] = __builtin_amdgcn_cvt_pk_fp8_f32(p0[4 * g + 2], p0[4 * g + 3], w, true);
;     int u = __builtin_amdgcn_cvt_pk_fp8_f32(p1[4 * g], p1[4 * g + 1], 0, false); p8[4 + g] = __builtin_amdgcn_cvt_pk_fp8_f32(p1[4 * g + 2], p1[4 * g + 3], u, true); }
; }
; __device__ __forceinline__ void pv8(f32x16* o, const char* Vt, const v8i32 p8, int r32, int hi) {
;   const int sw = (r32 >> 2) & 3, a0 = r32 * 64 + (((hi * 2) ^ sw) << 4), a1 = r32 * 64 + (((hi * 2 + 1) ^ sw) << 4);
; #pragma unroll
;   for (int d0 = 0; d0 < 4; ++d0) {
;     const v8i32 vf = cat8(*reinterpret_cast<const v4i32*>(Vt + d0 * 2048 + a0), *reinterpret_cast<const v4i32*>(Vt + d0 * 2048 + a1));
;     o[d0] = __builtin_amdgcn_mfma_scale_f32_32x32x64_f8f6f4(p8, vf, o[d0], 0, 0, 0, 127, 0, 127); }
; }
; __device__ __forceinline__ void qkt9(f32x16& p0, f32x16& p1, const char* Kn, const char* Kr, const v8i32* qf, const float init, int r32, int hi) {
; #pragma unroll
;   for (int r = 0; r < 16; ++r) { p0[r] = init; p1[r] = init; }
; #pragma unroll
;   for (int s = 0; s < 2; ++s) { const int c0 = s * 4 + hi * 2;
;     const v8i32 a0 = cat8(*reinterpret_cast<const v4i32*>(Kn + KN8SW(r32, c0)), *reinterpret_cast<const v4i32*>(Kn + KN8SW(r32, c0 + 1)));
;     const v8i32 a1 = cat8(*reinterpret_cast<const v4i32*>(Kn + 4096 + KN8SW(r32, c0)), *reinterpret_cast<const v4i32*>(Kn + 4096 + KN8SW(r32, c0 + 1)));
;     p0 = __builtin_amdgcn_mfma_scale_f32_32x32x64_f8f6f4(a0, qf[s], p0, 0, 0, 0, 127, 0, 124);
;     p1 = __builtin_amdgcn_mfma_scale_f32_32x32x64_f8f6f4(a1, qf[s], p1, 0, 0, 0, 127, 0, 124); }
;   { const int c0 = hi * 2;
.Lmla_q0_cont:
	ds_read_b128 v[82:85], v166 offset:16384
	ds_read_b128 v[86:89], v167 offset:16384
	ds_read_b128 v[222:225], v166 offset:20480
	ds_read_b128 v[226:229], v167 offset:20480
	v_exp_f32_e32 v0, v114
	v_exp_f32_e32 v177, v115
	v_exp_f32_e32 v179, v116
	v_exp_f32_e32 v254, v117
	v_add_f32_e32 v219, v0, v177
	v_cvt_pk_fp8_f32 v246, v0, v177
	v_add_f32_e32 v219, v179, v219
	v_add_f32_e32 v219, v254, v219
	v_cvt_pk_fp8_f32 v246, v179, v254 op_sel:[0,0,1]
	s_waitcnt lgkmcnt(2)
	v_mfma_scale_f32_32x32x64_f8f6f4 v[82:97], v[82:89], v[146:153], v[230:245], v194, v193 op_sel_hi:[0,0,0]
	v_exp_f32_e32 v0, v118
	v_exp_f32_e32 v177, v119
	v_exp_f32_e32 v179, v120
	v_exp_f32_e32 v254, v121
	v_add_f32_e32 v219, v0, v219
	v_add_f32_e32 v219, v177, v219
	v_cvt_pk_fp8_f32 v247, v0, v177
	v_add_f32_e32 v219, v179, v219
	v_add_f32_e32 v219, v254, v219
	v_cvt_pk_fp8_f32 v247, v179, v254 op_sel:[0,0,1]
	ds_read_b128 v[114:117], v168 offset:16384
	ds_read_b128 v[118:121], v169 offset:16384
	s_waitcnt lgkmcnt(2)
	v_mfma_scale_f32_32x32x64_f8f6f4 v[66:81], v[222:229], v[146:153], v[230:245], v194, v193 op_sel_hi:[0,0,0]
	ds_read_b128 v[222:225], v168 offset:20480
	ds_read_b128 v[226:229], v169 offset:20480
	v_exp_f32_e32 v0, v122
	v_exp_f32_e32 v177, v123
	v_exp_f32_e32 v179, v124
	v_exp_f32_e32 v254, v125
	v_add_f32_e32 v219, v0, v219
	v_add_f32_e32 v219, v177, v219
	v_cvt_pk_fp8_f32 v248, v0, v177
	v_add_f32_e32 v219, v179, v219
	v_add_f32_e32 v219, v254, v219
	v_cvt_pk_fp8_f32 v248, v179, v254 op_sel:[0,0,1]
	v_exp_f32_e32 v0, v126
	v_exp_f32_e32 v177, v127
	v_exp_f32_e32 v179, v128
	v_exp_f32_e32 v254, v129
	v_add_f32_e32 v219, v0, v219
	v_add_f32_e32 v219, v177, v219
	v_cvt_pk_fp8_f32 v249, v0, v177
	v_add_f32_e32 v219, v179, v219
	v_add_f32_e32 v219, v254, v219
	v_cvt_pk_fp8_f32 v249, v179, v254 op_sel:[0,0,1]
	ds_read_b128 v[122:125], v170 offset:32768
	ds_read_b128 v[126:129], v171 offset:32768
	s_waitcnt lgkmcnt(4)
	v_mfma_scale_f32_32x32x64_f8f6f4 v[82:97], v[114:121], v[138:145], v[82:97], v194, v193 op_sel_hi:[0,0,0]
	v_exp_f32_e32 v0, v98
	v_exp_f32_e32 v177, v99
	v_exp_f32_e32 v179, v100
	v_exp_f32_e32 v254, v101
	v_add_f32_e32 v219, v0, v219
	v_add_f32_e32 v219, v177, v219
	v_cvt_pk_fp8_f32 v250, v0, v177
	v_add_f32_e32 v219, v179, v219
	v_add_f32_e32 v219, v254, v219
	v_cvt_pk_fp8_f32 v250, v179, v254 op_sel:[0,0,1]
	s_waitcnt lgkmcnt(2)
	v_mfma_scale_f32_32x32x64_f8f6f4 v[66:81], v[222:229], v[138:145], v[66:81], v194, v193 op_sel_hi:[0,0,0]
	ds_read_b128 v[222:225], v170 offset:34816
	ds_read_b128 v[226:229], v171 offset:34816
	v_exp_f32_e32 v0, v102
	v_exp_f32_e32 v177, v103
	v_exp_f32_e32 v179, v104
	v_exp_f32_e32 v254, v105
	v_add_f32_e32 v219, v0, v219
	v_add_f32_e32 v219, v177, v219
	v_cvt_pk_fp8_f32 v251, v0, v177
	v_add_f32_e32 v219, v179, v219
	v_add_f32_e32 v219, v254, v219
	v_cvt_pk_fp8_f32 v251, v179, v254 op_sel:[0,0,1]
	v_exp_f32_e32 v0, v106
	v_exp_f32_e32 v177, v107
	v_exp_f32_e32 v179, v108
	v_exp_f32_e32 v254, v109
	v_add_f32_e32 v219, v0, v219
	v_add_f32_e32 v219, v177, v219
	v_cvt_pk_fp8_f32 v252, v0, v177
	v_add_f32_e32 v219, v179, v219
	v_add_f32_e32 v219, v254, v219
	v_cvt_pk_fp8_f32 v252, v179, v254 op_sel:[0,0,1]
	s_waitcnt lgkmcnt(2)
	v_mfma_scale_f32_32x32x64_f8f6f4 v[82:97], v[122:129], v[130:137], v[82:97], v194, v193 op_sel_hi:[0,0,0]
	v_exp_f32_e32 v0, v110
	v_exp_f32_e32 v177, v111
	v_exp_f32_e32 v179, v112
	v_exp_f32_e32 v254, v113
	v_add_f32_e32 v219, v0, v219
	v_add_f32_e32 v219, v177, v219
	v_cvt_pk_fp8_f32 v253, v0, v177
	v_add_f32_e32 v219, v179, v219
	v_add_f32_e32 v219, v254, v219
	v_cvt_pk_fp8_f32 v253, v179, v254 op_sel:[0,0,1]
	ds_read_b128 v[122:125], v185 offset:8192
	ds_read_b128 v[126:129], v186 offset:8192
	ds_read_b128 v[114:117], v185 offset:10240
	ds_read_b128 v[118:121], v186 offset:10240
	ds_read_b128 v[106:109], v185 offset:12288
	ds_read_b128 v[110:113], v186 offset:12288
	ds_read_b128 v[98:101], v185 offset:14336
	ds_read_b128 v[102:105], v186 offset:14336
	s_waitcnt lgkmcnt(8)
	v_mfma_scale_f32_32x32x64_f8f6f4 v[66:81], v[222:229], v[130:137], v[66:81], v194, v193 op_sel_hi:[0,0,0]
	v_mov_b32_e32 v0, v219
	s_nop 1
	v_permlane32_swap_b32_e32 v219, v0
	v_add_f32_e32 v219, v219, v0
	v_fma_f32 v209, v209, v221, v219
	v_max_f32_e32 v177, v82, v83
	v_max3_f32 v177, v177, v84, v85
	v_max3_f32 v177, v177, v86, v87
	v_max3_f32 v177, v177, v88, v89
	v_max3_f32 v177, v177, v90, v91
	v_max3_f32 v177, v177, v92, v93
	v_max3_f32 v177, v177, v94, v95
	v_max3_f32 v177, v177, v96, v97
	s_waitcnt lgkmcnt(6)
	v_mfma_scale_f32_32x32x64_f8f6f4 v[50:65], v[246:253], v[122:129], v[50:65], v194, v194 op_sel_hi:[0,0,0]
	s_waitcnt lgkmcnt(4)
	v_mfma_scale_f32_32x32x64_f8f6f4 v[34:49], v[246:253], v[114:121], v[34:49], v194, v194 op_sel_hi:[0,0,0]
	s_waitcnt vmcnt(0)
	s_waitcnt lgkmcnt(0)
	s_barrier
	s_waitcnt lgkmcnt(2)
	v_mfma_scale_f32_32x32x64_f8f6f4 v[18:33], v[246:253], v[106:113], v[18:33], v194, v194 op_sel_hi:[0,0,0]
	s_waitcnt lgkmcnt(0)
	v_mfma_scale_f32_32x32x64_f8f6f4 v[2:17], v[246:253], v[98:105], v[2:17], v194, v194 op_sel_hi:[0,0,0]
	v_max_f32_e32 v0, v66, v67
	v_max3_f32 v0, v0, v68, v69
	v_max3_f32 v0, v0, v70, v71
	v_max3_f32 v0, v0, v72, v73
	v_max3_f32 v0, v0, v74, v75
	v_max3_f32 v0, v0, v76, v77
	v_max3_f32 v0, v0, v78, v79
	v_max3_f32 v0, v0, v80, v81
	v_max_f32_e32 v177, v177, v0
	v_mov_b32_e32 v0, v177
	v_mov_b32_e32 v218, 1.0
	s_nop 0
	v_permlane32_swap_b32_e32 v177, v0
	v_max_f32_e32 v177, v177, v0
	v_cmp_ge_f32_e32 vcc, s90, v177
	s_cmp_eq_u64 vcc, exec
	s_cbranch_scc0 .Lmla_q1_newmax
